# v101 + second half of K-loop load-segment rebalancing (4/4/4/4): segment 4's last two LDS-DMA loads issue at the head of the next segment 1 (kept in segment 4 on the last iteration), segment-4 wait vm
# speedup vs baseline: 1.0121x; 1.0121x over previous
; #define PG8_STAGE(bufoff, gbase, voff) do { _Pragma("unroll") for (int _i = 0; _i < 2; ++_i) \
;         __builtin_amdgcn_global_load_lds((const unsigned*)((const char*)(gbase) + (voff)[_i]), (PG8_LAS unsigned*)(lds + (bufoff) + ldsw + _i * 8192), 16, 0, 0); } while (0)
; #define PG8_LDA(dst, b, h) do { _Pragma("unroll") for (int m = 0; m < 4; ++m) _Pragma("unroll") for (int k = 0; k < 2; ++k) dst[m][k] = *(const PG8_LAS bf16x8*)(lds + PG8_SA(b, h) + aoff + m * 2048 + k * 1024); } while (0)
; #define PG8_LDB(dst, b, h) do { _Pragma("unroll") for (int n = 0; n < 2; ++n) _Pragma("unroll") for (int k = 0; k < 2; ++k) dst[n][k] = *(const PG8_LAS bf16x8*)(lds + PG8_SB(b, h) + boff + n * 2048 + k * 1024); } while (0)
; #define PG8_MMA(ai, bj, At, Bt) do { __builtin_amdgcn_s_setprio(1); _Pragma("unroll") for (int m = 0; m < 4; ++m) _Pragma("unroll") for (int n = 0; n < 2; ++n) _Pragma("unroll") for (int k = 0; k < 2; ++k) \
;         acc[ai][bj][m][n] = __builtin_amdgcn_mfma_f32_16x16x32_bf16(Bt[n][k], At[m][k], acc[ai][bj][m][n], 0, 0, 0); __builtin_amdgcn_s_setprio(0); } while (0)
; #define PG8_WAIT_V(n) asm volatile("s_waitcnt vmcnt(" #n ")" ::: "memory")
; #define PG8_WAIT_L(n) asm volatile("s_waitcnt lgkmcnt(" #n ")" ::: "memory")
; #define PG8_BAR __builtin_amdgcn_s_barrier()
; template <class Epi, class Sched, bool ALIGN_EPI = false, bool SP2 = false>
; __device__ __forceinline__ void gemm_phase(PG8_LAS unsigned char* lds, const Gemm g, const Sched& S, const Epi& E) {
;     ...
;             const char* a1 = cA + (size_t)(t + 1) * kstep;
;             const char* a2 = last ? nA : cA + (size_t)(t + 2) * kstep; const char* b2 = last ? nB : cB + (size_t)(t + 2) * kstep;
;             const char* a3 = a2 + kstep; const char* b3 = b2 + kstep;
;             if (last && has_next) S.a_ready(nxt);
;             if constexpr (SP2) {
;             PG8_LDB(B0, 0, 0); PG8_LDB(B1, 0, 1); PG8_SCHED; PG8_LDA(At, 0, 0); PG8_STAGE(PG8_SA(1, 1), a1 + hstep, voffA);
;             PG8_WAIT_V(8); PG8_WAIT_L(0); PG8_BAR; PG8_MMA(0, 0, At, B0); PG8_MMA(0, 1, At, B1); PG8_BAR; PG8_SCHED;
;             PG8_LDA(At, 0, 1); PG8_STAGE(PG8_SB(0, 0), b2, voffB); PG8_STAGE(PG8_SB(0, 1), b2 + hstep, voffB); PG8_STAGE(PG8_SA(0, 0), a2, voffA);
;             PG8_WAIT_V(8); PG8_WAIT_L(0); PG8_BAR; PG8_MMA(1, 0, At, B0); PG8_MMA(1, 1, At, B1); PG8_BAR; PG8_SCHED;
.LBB0_100:
	s_add_u32 s28, s8, 0xfffc0080
	s_addc_u32 s29, s9, -1
	s_cmp_eq_u32 s45, 12
	s_cselect_b32 s31, s3, s29
	s_cselect_b32 s30, s7, s28
	s_cselect_b32 s29, s11, s44
	s_cselect_b32 s28, s21, s23
	s_add_i32 m0, s50, 0xffffff80
	ds_read_b128 v[132:135], v204
	ds_read_b128 v[136:139], v204 offset:1024
	ds_read_b128 v[140:143], v204 offset:2048
	ds_read_b128 v[144:147], v204 offset:3072
	ds_read_b128 v[148:151], v204 offset:16384
	ds_read_b128 v[152:155], v204 offset:17408
	ds_read_b128 v[156:159], v204 offset:18432
	ds_read_b128 v[160:163], v204 offset:19456
	global_load_lds_dwordx4 v[224:225], off offset:128
	s_add_i32 m0, s51, 0xffffff80
	v_lshl_add_u64 v[194:195], s[8:9], 0, v[178:179]
	global_load_lds_dwordx4 v[226:227], off offset:128
	s_add_i32 m0, s42, 0xc000
	ds_read_b128 v[164:167], v205
	ds_read_b128 v[182:185], v205 offset:1024
	ds_read_b128 v[186:189], v205 offset:2048
	ds_read_b128 v[190:193], v205 offset:3072
	ds_read_b128 v[208:211], v205 offset:4096
	ds_read_b128 v[212:215], v205 offset:5120
	ds_read_b128 v[216:219], v205 offset:6144
	ds_read_b128 v[220:223], v205 offset:7168
	global_load_lds_dwordx4 v[194:195], off
	s_add_i32 m0, s42, 0xe000
	v_lshl_add_u64 v[194:195], s[8:9], 0, v[180:181]
	global_load_lds_dwordx4 v[194:195], off
	s_waitcnt vmcnt(8) lgkmcnt(0)
	s_barrier
	s_setprio 1
	v_mfma_f32_16x16x32_bf16 v[128:131], v[132:135], v[164:167], v[128:131]
	v_mfma_f32_16x16x32_bf16 v[124:127], v[140:143], v[164:167], v[124:127]
	v_mfma_f32_16x16x32_bf16 v[112:115], v[132:135], v[186:189], v[112:115]
	v_mfma_f32_16x16x32_bf16 v[108:111], v[140:143], v[186:189], v[108:111]
	v_mfma_f32_16x16x32_bf16 v[96:99], v[132:135], v[208:211], v[96:99]
	v_mfma_f32_16x16x32_bf16 v[92:95], v[140:143], v[208:211], v[92:95]
	v_mfma_f32_16x16x32_bf16 v[80:83], v[132:135], v[216:219], v[80:83]
	v_mfma_f32_16x16x32_bf16 v[76:79], v[140:143], v[216:219], v[76:79]
	v_mfma_f32_16x16x32_bf16 v[128:131], v[136:139], v[182:185], v[128:131]
	v_mfma_f32_16x16x32_bf16 v[124:127], v[144:147], v[182:185], v[124:127]
	v_mfma_f32_16x16x32_bf16 v[112:115], v[136:139], v[190:193], v[112:115]
	v_mfma_f32_16x16x32_bf16 v[108:111], v[144:147], v[190:193], v[108:111]
	v_mfma_f32_16x16x32_bf16 v[96:99], v[136:139], v[212:215], v[96:99]
	v_mfma_f32_16x16x32_bf16 v[92:95], v[144:147], v[212:215], v[92:95]
	v_mfma_f32_16x16x32_bf16 v[80:83], v[136:139], v[220:223], v[80:83]
	v_mfma_f32_16x16x32_bf16 v[76:79], v[144:147], v[220:223], v[76:79]
	s_setprio 0
	s_setprio 1
	v_mfma_f32_16x16x32_bf16 v[120:123], v[148:151], v[164:167], v[120:123]
	v_mfma_f32_16x16x32_bf16 v[116:119], v[156:159], v[164:167], v[116:119]
	v_mfma_f32_16x16x32_bf16 v[104:107], v[148:151], v[186:189], v[104:107]
	v_mfma_f32_16x16x32_bf16 v[100:103], v[156:159], v[186:189], v[100:103]
	v_mfma_f32_16x16x32_bf16 v[88:91], v[148:151], v[208:211], v[88:91]
	v_mfma_f32_16x16x32_bf16 v[84:87], v[156:159], v[208:211], v[84:87]
	v_mfma_f32_16x16x32_bf16 v[72:75], v[148:151], v[216:219], v[72:75]
	v_mfma_f32_16x16x32_bf16 v[68:71], v[156:159], v[216:219], v[68:71]
	v_mfma_f32_16x16x32_bf16 v[120:123], v[152:155], v[182:185], v[120:123]
	v_mfma_f32_16x16x32_bf16 v[116:119], v[160:163], v[182:185], v[116:119]
	v_mfma_f32_16x16x32_bf16 v[104:107], v[152:155], v[190:193], v[104:107]
	v_mfma_f32_16x16x32_bf16 v[100:103], v[160:163], v[190:193], v[100:103]
	v_mfma_f32_16x16x32_bf16 v[88:91], v[152:155], v[212:215], v[88:91]
	v_mfma_f32_16x16x32_bf16 v[84:87], v[160:163], v[212:215], v[84:87]
	v_mfma_f32_16x16x32_bf16 v[72:75], v[152:155], v[220:223], v[72:75]
	v_mfma_f32_16x16x32_bf16 v[68:71], v[160:163], v[220:223], v[68:71]
	s_setprio 0
	s_barrier
	v_lshl_add_u64 v[194:195], s[28:29], 0, v[168:169]
	s_add_i32 m0, s41, 0x10000
	ds_read_b128 v[164:167], v205 offset:16384
	ds_read_b128 v[182:185], v205 offset:17408
	ds_read_b128 v[186:189], v205 offset:18432
	ds_read_b128 v[190:193], v205 offset:19456
	ds_read_b128 v[208:211], v205 offset:20480
	ds_read_b128 v[212:215], v205 offset:21504
	ds_read_b128 v[216:219], v205 offset:22528
	ds_read_b128 v[220:223], v205 offset:23552
	global_load_lds_dwordx4 v[194:195], off
	s_add_i32 m0, s41, 0x12000
	s_add_u32 s54, s28, 0x40000
	v_lshl_add_u64 v[202:203], s[28:29], 0, v[172:173]
	s_addc_u32 s55, s29, 0
	global_load_lds_dwordx4 v[202:203], off
	v_lshl_add_u64 v[224:225], s[54:55], 0, v[168:169]
	s_add_i32 m0, s41, 0x14000
	v_lshl_add_u64 v[226:227], s[30:31], 0, v[170:171]
	global_load_lds_dwordx4 v[224:225], off
	s_add_i32 m0, s41, 0x16000
	v_lshl_add_u64 v[224:225], s[54:55], 0, v[172:173]
	global_load_lds_dwordx4 v[224:225], off
	v_lshl_add_u64 v[224:225], s[30:31], 0, v[0:1]
	s_waitcnt vmcnt(6) lgkmcnt(0)
	s_barrier
	s_setprio 1
	v_mfma_f32_16x16x32_bf16 v[64:67], v[132:135], v[164:167], v[64:67]
	v_mfma_f32_16x16x32_bf16 v[60:63], v[140:143], v[164:167], v[60:63]
	v_mfma_f32_16x16x32_bf16 v[48:51], v[132:135], v[186:189], v[48:51]
	v_mfma_f32_16x16x32_bf16 v[44:47], v[140:143], v[186:189], v[44:47]
	v_mfma_f32_16x16x32_bf16 v[32:35], v[132:135], v[208:211], v[32:35]
	v_mfma_f32_16x16x32_bf16 v[28:31], v[140:143], v[208:211], v[28:31]
	v_mfma_f32_16x16x32_bf16 v[16:19], v[132:135], v[216:219], v[16:19]
	v_mfma_f32_16x16x32_bf16 v[12:15], v[140:143], v[216:219], v[12:15]
	v_mfma_f32_16x16x32_bf16 v[64:67], v[136:139], v[182:185], v[64:67]
	v_mfma_f32_16x16x32_bf16 v[60:63], v[144:147], v[182:185], v[60:63]
	v_mfma_f32_16x16x32_bf16 v[48:51], v[136:139], v[190:193], v[48:51]
	v_mfma_f32_16x16x32_bf16 v[44:47], v[144:147], v[190:193], v[44:47]
	v_mfma_f32_16x16x32_bf16 v[32:35], v[136:139], v[212:215], v[32:35]
	v_mfma_f32_16x16x32_bf16 v[28:31], v[144:147], v[212:215], v[28:31]
	v_mfma_f32_16x16x32_bf16 v[16:19], v[136:139], v[220:223], v[16:19]
	v_mfma_f32_16x16x32_bf16 v[12:15], v[144:147], v[220:223], v[12:15]
	s_setprio 0
	s_setprio 1
	v_mfma_f32_16x16x32_bf16 v[56:59], v[148:151], v[164:167], v[56:59]
	v_mfma_f32_16x16x32_bf16 v[52:55], v[156:159], v[164:167], v[52:55]
	v_mfma_f32_16x16x32_bf16 v[40:43], v[148:151], v[186:189], v[40:43]
	v_mfma_f32_16x16x32_bf16 v[36:39], v[156:159], v[186:189], v[36:39]
	v_mfma_f32_16x16x32_bf16 v[24:27], v[148:151], v[208:211], v[24:27]
	v_mfma_f32_16x16x32_bf16 v[20:23], v[156:159], v[208:211], v[20:23]
	v_mfma_f32_16x16x32_bf16 v[8:11], v[148:151], v[216:219], v[8:11]
	v_mfma_f32_16x16x32_bf16 v[4:7], v[156:159], v[216:219], v[4:7]
	v_mfma_f32_16x16x32_bf16 v[56:59], v[152:155], v[182:185], v[56:59]
	v_mfma_f32_16x16x32_bf16 v[52:55], v[160:163], v[182:185], v[52:55]
	v_mfma_f32_16x16x32_bf16 v[40:43], v[152:155], v[190:193], v[40:43]
	v_mfma_f32_16x16x32_bf16 v[36:39], v[160:163], v[190:193], v[36:39]
	v_mfma_f32_16x16x32_bf16 v[24:27], v[152:155], v[212:215], v[24:27]
	v_mfma_f32_16x16x32_bf16 v[20:23], v[160:163], v[212:215], v[20:23]
	v_mfma_f32_16x16x32_bf16 v[8:11], v[152:155], v[220:223], v[8:11]
	v_mfma_f32_16x16x32_bf16 v[4:7], v[160:163], v[220:223], v[4:7]
	s_setprio 0
	s_barrier
; #define PG8_STAGE(bufoff, gbase, voff) do { _Pragma("unroll") for (int _i = 0; _i < 2; ++_i) \
;         __builtin_amdgcn_global_load_lds((const unsigned*)((const char*)(gbase) + (voff)[_i]), (PG8_LAS unsigned*)(lds + (bufoff) + ldsw + _i * 8192), 16, 0, 0); } while (0)
; #define PG8_LDA(dst, b, h) do { _Pragma("unroll") for (int m = 0; m < 4; ++m) _Pragma("unroll") for (int k = 0; k < 2; ++k) dst[m][k] = *(const PG8_LAS bf16x8*)(lds + PG8_SA(b, h) + aoff + m * 2048 + k * 1024); } while (0)
; #define PG8_LDB(dst, b, h) do { _Pragma("unroll") for (int n = 0; n < 2; ++n) _Pragma("unroll") for (int k = 0; k < 2; ++k) dst[n][k] = *(const PG8_LAS bf16x8*)(lds + PG8_SB(b, h) + boff + n * 2048 + k * 1024); } while (0)
; #define PG8_MMA(ai, bj, At, Bt) do { __builtin_amdgcn_s_setprio(1); _Pragma("unroll") for (int m = 0; m < 4; ++m) _Pragma("unroll") for (int n = 0; n < 2; ++n) _Pragma("unroll") for (int k = 0; k < 2; ++k) \
;         acc[ai][bj][m][n] = __builtin_amdgcn_mfma_f32_16x16x32_bf16(Bt[n][k], At[m][k], acc[ai][bj][m][n], 0, 0, 0); __builtin_amdgcn_s_setprio(0); } while (0)
; #define PG8_WAIT_V(n) asm volatile("s_waitcnt vmcnt(" #n ")" ::: "memory")
; #define PG8_WAIT_L(n) asm volatile("s_waitcnt lgkmcnt(" #n ")" ::: "memory")
; #define PG8_BAR __builtin_amdgcn_s_barrier()
; #define PG8_SCHED __builtin_amdgcn_sched_barrier(0)
; template <class Epi, class Sched, bool ALIGN_EPI = false, bool SP2 = false>
; __device__ __forceinline__ void gemm_phase(PG8_LAS unsigned char* lds, const Gemm g, const Sched& S, const Epi& E) {
;     ...
;             PG8_LDB(B0, 1, 0); PG8_LDB(B1, 1, 1); PG8_SCHED; PG8_LDA(At, 1, 0); PG8_STAGE(PG8_SA(0, 1), a2 + hstep, voffA);
;             PG8_WAIT_V(8); PG8_WAIT_L(0); PG8_BAR; PG8_MMA(0, 0, At, B0); PG8_MMA(0, 1, At, B1); PG8_BAR; PG8_SCHED;
;             PG8_LDA(At, 1, 1); PG8_STAGE(PG8_SB(1, 0), b3, voffB); PG8_STAGE(PG8_SB(1, 1), b3 + hstep, voffB); PG8_STAGE(PG8_SA(1, 0), a3, voffA);
;             PG8_WAIT_V(8); PG8_WAIT_L(0); PG8_BAR; PG8_MMA(1, 0, At, B0); PG8_MMA(1, 1, At, B1); PG8_BAR; PG8_SCHED;
.Lkmid_0:
	ds_read_b128 v[132:135], v204 offset:32768
	ds_read_b128 v[136:139], v204 offset:33792
	ds_read_b128 v[140:143], v204 offset:34816
	ds_read_b128 v[144:147], v204 offset:35840
	ds_read_b128 v[148:151], v204 offset:49152
	ds_read_b128 v[152:155], v204 offset:50176
	ds_read_b128 v[156:159], v204 offset:51200
	ds_read_b128 v[160:163], v204 offset:52224
	s_mov_b32 m0, s42
	s_add_u32 s30, s30, 0x40000
	s_addc_u32 s31, s31, 0
	global_load_lds_dwordx4 v[224:225], off
	s_mov_b32 m0, s43
	v_lshl_add_u64 v[228:229], s[30:31], 0, v[0:1]
	global_load_lds_dwordx4 v[226:227], off
	s_mov_b32 m0, s46
	ds_read_b128 v[164:167], v205 offset:32768
	ds_read_b128 v[182:185], v205 offset:33792
	ds_read_b128 v[186:189], v205 offset:34816
	ds_read_b128 v[190:193], v205 offset:35840
	ds_read_b128 v[208:211], v205 offset:36864
	ds_read_b128 v[212:215], v205 offset:37888
	ds_read_b128 v[216:219], v205 offset:38912
	ds_read_b128 v[220:223], v205 offset:39936
	global_load_lds_dwordx4 v[228:229], off
	s_mov_b32 m0, s47
	v_lshl_add_u64 v[228:229], s[30:31], 0, v[170:171]
	global_load_lds_dwordx4 v[228:229], off
	s_waitcnt vmcnt(8) lgkmcnt(0)
	s_barrier
	s_setprio 1
	v_mfma_f32_16x16x32_bf16 v[128:131], v[132:135], v[164:167], v[128:131]
	v_mfma_f32_16x16x32_bf16 v[124:127], v[140:143], v[164:167], v[124:127]
	v_mfma_f32_16x16x32_bf16 v[112:115], v[132:135], v[186:189], v[112:115]
	v_mfma_f32_16x16x32_bf16 v[108:111], v[140:143], v[186:189], v[108:111]
	v_mfma_f32_16x16x32_bf16 v[96:99], v[132:135], v[208:211], v[96:99]
	v_mfma_f32_16x16x32_bf16 v[92:95], v[140:143], v[208:211], v[92:95]
	v_mfma_f32_16x16x32_bf16 v[80:83], v[132:135], v[216:219], v[80:83]
	v_mfma_f32_16x16x32_bf16 v[76:79], v[140:143], v[216:219], v[76:79]
	v_mfma_f32_16x16x32_bf16 v[128:131], v[136:139], v[182:185], v[128:131]
	v_mfma_f32_16x16x32_bf16 v[124:127], v[144:147], v[182:185], v[124:127]
	v_mfma_f32_16x16x32_bf16 v[112:115], v[136:139], v[190:193], v[112:115]
	v_mfma_f32_16x16x32_bf16 v[108:111], v[144:147], v[190:193], v[108:111]
	v_mfma_f32_16x16x32_bf16 v[96:99], v[136:139], v[212:215], v[96:99]
	v_mfma_f32_16x16x32_bf16 v[92:95], v[144:147], v[212:215], v[92:95]
	v_mfma_f32_16x16x32_bf16 v[80:83], v[136:139], v[220:223], v[80:83]
	v_mfma_f32_16x16x32_bf16 v[76:79], v[144:147], v[220:223], v[76:79]
	s_setprio 0
	s_setprio 1
	v_mfma_f32_16x16x32_bf16 v[120:123], v[148:151], v[164:167], v[120:123]
	v_mfma_f32_16x16x32_bf16 v[116:119], v[156:159], v[164:167], v[116:119]
	v_mfma_f32_16x16x32_bf16 v[104:107], v[148:151], v[186:189], v[104:107]
	v_mfma_f32_16x16x32_bf16 v[100:103], v[156:159], v[186:189], v[100:103]
	v_mfma_f32_16x16x32_bf16 v[88:91], v[148:151], v[208:211], v[88:91]
	v_mfma_f32_16x16x32_bf16 v[84:87], v[156:159], v[208:211], v[84:87]
	v_mfma_f32_16x16x32_bf16 v[72:75], v[148:151], v[216:219], v[72:75]
	v_mfma_f32_16x16x32_bf16 v[68:71], v[156:159], v[216:219], v[68:71]
	v_mfma_f32_16x16x32_bf16 v[120:123], v[152:155], v[182:185], v[120:123]
	v_mfma_f32_16x16x32_bf16 v[116:119], v[160:163], v[182:185], v[116:119]
	v_mfma_f32_16x16x32_bf16 v[104:107], v[152:155], v[190:193], v[104:107]
	v_mfma_f32_16x16x32_bf16 v[100:103], v[160:163], v[190:193], v[100:103]
	v_mfma_f32_16x16x32_bf16 v[88:91], v[152:155], v[212:215], v[88:91]
	v_mfma_f32_16x16x32_bf16 v[84:87], v[160:163], v[212:215], v[84:87]
	v_mfma_f32_16x16x32_bf16 v[72:75], v[152:155], v[220:223], v[72:75]
	v_mfma_f32_16x16x32_bf16 v[68:71], v[160:163], v[220:223], v[68:71]
	s_setprio 0
	s_barrier
	s_add_i32 m0, s41, 0x17f80
	ds_read_b128 v[164:167], v205 offset:49152
	ds_read_b128 v[182:185], v205 offset:50176
	ds_read_b128 v[186:189], v205 offset:51200
	ds_read_b128 v[190:193], v205 offset:52224
	ds_read_b128 v[208:211], v205 offset:53248
	ds_read_b128 v[212:215], v205 offset:54272
	ds_read_b128 v[216:219], v205 offset:55296
	ds_read_b128 v[220:223], v205 offset:56320
	global_load_lds_dwordx4 v[194:195], off offset:128
	s_add_i32 m0, s41, 0x19f80
	s_add_u32 s28, s28, 0x40080
	s_addc_u32 s29, s29, 0
	global_load_lds_dwordx4 v[202:203], off offset:128
	s_add_i32 m0, s41, 0x1c000
	v_lshl_add_u64 v[194:195], s[28:29], 0, v[168:169]
	global_load_lds_dwordx4 v[194:195], off
	s_add_i32 m0, s41, 0x1e000
	v_lshl_add_u64 v[194:195], s[28:29], 0, v[172:173]
	global_load_lds_dwordx4 v[194:195], off
	s_cmp_eq_u32 s45, 12
	s_cbranch_scc0 .Lks4_0
	s_add_i32 m0, s50, 0xffffff80
	s_nop 0
	global_load_lds_dwordx4 v[224:225], off offset:128
	s_add_i32 m0, s51, 0xffffff80
	s_nop 0
	global_load_lds_dwordx4 v[226:227], off offset:128
; #define PG8_STAGE(bufoff, gbase, voff) do { _Pragma("unroll") for (int _i = 0; _i < 2; ++_i) \
;         __builtin_amdgcn_global_load_lds((const unsigned*)((const char*)(gbase) + (voff)[_i]), (PG8_LAS unsigned*)(lds + (bufoff) + ldsw + _i * 8192), 16, 0, 0); } while (0)
; #define PG8_LDA(dst, b, h) do { _Pragma("unroll") for (int m = 0; m < 4; ++m) _Pragma("unroll") for (int k = 0; k < 2; ++k) dst[m][k] = *(const PG8_LAS bf16x8*)(lds + PG8_SA(b, h) + aoff + m * 2048 + k * 1024); } while (0)
; #define PG8_MMA(ai, bj, At, Bt) do { __builtin_amdgcn_s_setprio(1); _Pragma("unroll") for (int m = 0; m < 4; ++m) _Pragma("unroll") for (int n = 0; n < 2; ++n) _Pragma("unroll") for (int k = 0; k < 2; ++k) \
;         acc[ai][bj][m][n] = __builtin_amdgcn_mfma_f32_16x16x32_bf16(Bt[n][k], At[m][k], acc[ai][bj][m][n], 0, 0, 0); __builtin_amdgcn_s_setprio(0); } while (0)
; #define PG8_WAIT_V(n) asm volatile("s_waitcnt vmcnt(" #n ")" ::: "memory")
; #define PG8_WAIT_L(n) asm volatile("s_waitcnt lgkmcnt(" #n ")" ::: "memory")
; #define PG8_BAR __builtin_amdgcn_s_barrier()
; #define PG8_SCHED __builtin_amdgcn_sched_barrier(0)
; template <class Epi, class Sched, bool ALIGN_EPI = false, bool SP2 = false>
; __device__ __forceinline__ void gemm_phase(PG8_LAS unsigned char* lds, const Gemm g, const Sched& S, const Epi& E) {
;     ...
;         for (int t = 0; t < nt; t += 2) {
;     ...
;             PG8_LDA(At, 1, 1); PG8_STAGE(PG8_SB(1, 0), b3, voffB); PG8_STAGE(PG8_SB(1, 1), b3 + hstep, voffB); PG8_STAGE(PG8_SA(1, 0), a3, voffA);
;             PG8_WAIT_V(8); PG8_WAIT_L(0); PG8_BAR; PG8_MMA(1, 0, At, B0); PG8_MMA(1, 1, At, B1); PG8_BAR; PG8_SCHED;
.Lks4_0:
	s_add_u32 s8, s8, 0x100
	s_addc_u32 s9, s9, 0
	s_add_u32 s23, s23, 0x100
	s_addc_u32 s44, s44, 0
	s_waitcnt vmcnt(6) lgkmcnt(0)
	s_barrier
	s_setprio 1
	v_mfma_f32_16x16x32_bf16 v[64:67], v[132:135], v[164:167], v[64:67]
	v_mfma_f32_16x16x32_bf16 v[60:63], v[140:143], v[164:167], v[60:63]
	v_mfma_f32_16x16x32_bf16 v[48:51], v[132:135], v[186:189], v[48:51]
	v_mfma_f32_16x16x32_bf16 v[44:47], v[140:143], v[186:189], v[44:47]
	v_mfma_f32_16x16x32_bf16 v[32:35], v[132:135], v[208:211], v[32:35]
	v_mfma_f32_16x16x32_bf16 v[28:31], v[140:143], v[208:211], v[28:31]
	v_mfma_f32_16x16x32_bf16 v[16:19], v[132:135], v[216:219], v[16:19]
	v_mfma_f32_16x16x32_bf16 v[12:15], v[140:143], v[216:219], v[12:15]
	v_mfma_f32_16x16x32_bf16 v[64:67], v[136:139], v[182:185], v[64:67]
	v_mfma_f32_16x16x32_bf16 v[60:63], v[144:147], v[182:185], v[60:63]
	v_mfma_f32_16x16x32_bf16 v[48:51], v[136:139], v[190:193], v[48:51]
	v_mfma_f32_16x16x32_bf16 v[44:47], v[144:147], v[190:193], v[44:47]
	v_mfma_f32_16x16x32_bf16 v[32:35], v[136:139], v[212:215], v[32:35]
	v_mfma_f32_16x16x32_bf16 v[28:31], v[144:147], v[212:215], v[28:31]
	v_mfma_f32_16x16x32_bf16 v[16:19], v[136:139], v[220:223], v[16:19]
	v_mfma_f32_16x16x32_bf16 v[12:15], v[144:147], v[220:223], v[12:15]
	s_setprio 0
	s_setprio 1
	v_mfma_f32_16x16x32_bf16 v[56:59], v[148:151], v[164:167], v[56:59]
	v_mfma_f32_16x16x32_bf16 v[52:55], v[156:159], v[164:167], v[52:55]
	v_mfma_f32_16x16x32_bf16 v[40:43], v[148:151], v[186:189], v[40:43]
	v_mfma_f32_16x16x32_bf16 v[36:39], v[156:159], v[186:189], v[36:39]
	v_mfma_f32_16x16x32_bf16 v[24:27], v[148:151], v[208:211], v[24:27]
	v_mfma_f32_16x16x32_bf16 v[20:23], v[156:159], v[208:211], v[20:23]
	v_mfma_f32_16x16x32_bf16 v[8:11], v[148:151], v[216:219], v[8:11]
	v_mfma_f32_16x16x32_bf16 v[4:7], v[156:159], v[216:219], v[4:7]
	v_mfma_f32_16x16x32_bf16 v[56:59], v[152:155], v[182:185], v[56:59]
	v_mfma_f32_16x16x32_bf16 v[52:55], v[160:163], v[182:185], v[52:55]
	v_mfma_f32_16x16x32_bf16 v[40:43], v[152:155], v[190:193], v[40:43]
	v_mfma_f32_16x16x32_bf16 v[36:39], v[160:163], v[190:193], v[36:39]
	v_mfma_f32_16x16x32_bf16 v[24:27], v[152:155], v[212:215], v[24:27]
	v_mfma_f32_16x16x32_bf16 v[20:23], v[160:163], v[212:215], v[20:23]
	v_mfma_f32_16x16x32_bf16 v[8:11], v[152:155], v[220:223], v[8:11]
	v_mfma_f32_16x16x32_bf16 v[4:7], v[160:163], v[220:223], v[4:7]
	s_setprio 0
	s_barrier
	s_add_i32 s45, s45, 2
	s_cmp_gt_u32 s45, 13
	s_cbranch_scc0 .LBB0_100
	s_and_b64 vcc, exec, s[14:15]
	s_cbranch_vccz .LBB0_103
	s_barrier

; #define PG8_STAGE(bufoff, gbase, voff) do { _Pragma("unroll") for (int _i = 0; _i < 2; ++_i) \
;         __builtin_amdgcn_global_load_lds((const unsigned*)((const char*)(gbase) + (voff)[_i]), (PG8_LAS unsigned*)(lds + (bufoff) + ldsw + _i * 8192), 16, 0, 0); } while (0)
; #define PG8_LDA(dst, b, h) do { _Pragma("unroll") for (int m = 0; m < 4; ++m) _Pragma("unroll") for (int k = 0; k < 2; ++k) dst[m][k] = *(const PG8_LAS bf16x8*)(lds + PG8_SA(b, h) + aoff + m * 2048 + k * 1024); } while (0)
; #define PG8_LDB(dst, b, h) do { _Pragma("unroll") for (int n = 0; n < 2; ++n) _Pragma("unroll") for (int k = 0; k < 2; ++k) dst[n][k] = *(const PG8_LAS bf16x8*)(lds + PG8_SB(b, h) + boff + n * 2048 + k * 1024); } while (0)
; #define PG8_MMA(ai, bj, At, Bt) do { __builtin_amdgcn_s_setprio(1); _Pragma("unroll") for (int m = 0; m < 4; ++m) _Pragma("unroll") for (int n = 0; n < 2; ++n) _Pragma("unroll") for (int k = 0; k < 2; ++k) \
;         acc[ai][bj][m][n] = __builtin_amdgcn_mfma_f32_16x16x32_bf16(Bt[n][k], At[m][k], acc[ai][bj][m][n], 0, 0, 0); __builtin_amdgcn_s_setprio(0); } while (0)
; #define PG8_WAIT_V(n) asm volatile("s_waitcnt vmcnt(" #n ")" ::: "memory")
; #define PG8_WAIT_L(n) asm volatile("s_waitcnt lgkmcnt(" #n ")" ::: "memory")
; #define PG8_BAR __builtin_amdgcn_s_barrier()
; template <class Epi, class Sched, bool ALIGN_EPI = false, bool SP2 = false>
; __device__ __forceinline__ void gemm_phase(PG8_LAS unsigned char* lds, const Gemm g, const Sched& S, const Epi& E) {
;     ...
;             const char* a1 = cA + (size_t)(t + 1) * kstep;
;             const char* a2 = last ? nA : cA + (size_t)(t + 2) * kstep; const char* b2 = last ? nB : cB + (size_t)(t + 2) * kstep;
;             const char* a3 = a2 + kstep; const char* b3 = b2 + kstep;
;             if (last && has_next) S.a_ready(nxt);
;             if constexpr (SP2) {
;             PG8_LDB(B0, 0, 0); PG8_LDB(B1, 0, 1); PG8_SCHED; PG8_LDA(At, 0, 0); PG8_STAGE(PG8_SA(1, 1), a1 + hstep, voffA);
;             PG8_WAIT_V(8); PG8_WAIT_L(0); PG8_BAR; PG8_MMA(0, 0, At, B0); PG8_MMA(0, 1, At, B1); PG8_BAR; PG8_SCHED;
;             PG8_LDA(At, 0, 1); PG8_STAGE(PG8_SB(0, 0), b2, voffB); PG8_STAGE(PG8_SB(0, 1), b2 + hstep, voffB); PG8_STAGE(PG8_SA(0, 0), a2, voffA);
;             PG8_WAIT_V(8); PG8_WAIT_L(0); PG8_BAR; PG8_MMA(1, 0, At, B0); PG8_MMA(1, 1, At, B1); PG8_BAR; PG8_SCHED;
.LBB0_329:
	s_add_u32 s30, s28, 0xfffc0080
	s_addc_u32 s31, s29, -1
	s_cmp_eq_u32 s45, 12
	s_cselect_b32 s35, s3, s31
	s_cselect_b32 s34, s17, s30
	s_cselect_b32 s31, s19, s44
	s_cselect_b32 s30, s25, s27
	s_add_i32 m0, s49, 0xffffff80
	ds_read_b128 v[108:111], v251
	ds_read_b128 v[112:115], v251 offset:1024
	ds_read_b128 v[124:127], v251 offset:2048
	ds_read_b128 v[128:131], v251 offset:3072
	ds_read_b128 v[132:135], v251 offset:16384
	ds_read_b128 v[140:143], v251 offset:17408
	ds_read_b128 v[148:151], v251 offset:18432
	ds_read_b128 v[156:159], v251 offset:19456
	global_load_lds_dwordx4 v[216:217], off offset:128
	s_add_i32 m0, s50, 0xffffff80
	v_lshl_add_u64 v[212:213], s[28:29], 0, v[208:209]
	global_load_lds_dwordx4 v[218:219], off offset:128
	s_add_i32 m0, s42, 0xc000
	ds_read_b128 v[164:167], v253
	ds_read_b128 v[168:171], v253 offset:1024
	ds_read_b128 v[172:175], v253 offset:2048
	ds_read_b128 v[176:179], v253 offset:3072
	ds_read_b128 v[180:183], v253 offset:4096
	ds_read_b128 v[184:187], v253 offset:5120
	ds_read_b128 v[188:191], v253 offset:6144
	ds_read_b128 v[192:195], v253 offset:7168
	global_load_lds_dwordx4 v[212:213], off
	s_add_i32 m0, s42, 0xe000
	v_lshl_add_u64 v[212:213], s[28:29], 0, v[210:211]
	global_load_lds_dwordx4 v[212:213], off
	s_waitcnt vmcnt(8) lgkmcnt(0)
	s_barrier
	s_setprio 1
	v_mfma_f32_16x16x32_bf16 v[160:163], v[108:111], v[164:167], v[160:163]
	v_mfma_f32_16x16x32_bf16 v[152:155], v[124:127], v[164:167], v[152:155]
	v_mfma_f32_16x16x32_bf16 v[120:123], v[108:111], v[172:175], v[120:123]
	v_mfma_f32_16x16x32_bf16 v[116:119], v[124:127], v[172:175], v[116:119]
	v_mfma_f32_16x16x32_bf16 v[96:99], v[108:111], v[180:183], v[96:99]
	v_mfma_f32_16x16x32_bf16 v[92:95], v[124:127], v[180:183], v[92:95]
	v_mfma_f32_16x16x32_bf16 v[80:83], v[108:111], v[188:191], v[80:83]
	v_mfma_f32_16x16x32_bf16 v[76:79], v[124:127], v[188:191], v[76:79]
	v_mfma_f32_16x16x32_bf16 v[160:163], v[112:115], v[168:171], v[160:163]
	v_mfma_f32_16x16x32_bf16 v[152:155], v[128:131], v[168:171], v[152:155]
	v_mfma_f32_16x16x32_bf16 v[120:123], v[112:115], v[176:179], v[120:123]
	v_mfma_f32_16x16x32_bf16 v[116:119], v[128:131], v[176:179], v[116:119]
	v_mfma_f32_16x16x32_bf16 v[96:99], v[112:115], v[184:187], v[96:99]
	v_mfma_f32_16x16x32_bf16 v[92:95], v[128:131], v[184:187], v[92:95]
	v_mfma_f32_16x16x32_bf16 v[80:83], v[112:115], v[192:195], v[80:83]
	v_mfma_f32_16x16x32_bf16 v[76:79], v[128:131], v[192:195], v[76:79]
	s_setprio 0
	s_setprio 1
	v_mfma_f32_16x16x32_bf16 v[144:147], v[132:135], v[164:167], v[144:147]
	v_mfma_f32_16x16x32_bf16 v[136:139], v[148:151], v[164:167], v[136:139]
	v_mfma_f32_16x16x32_bf16 v[104:107], v[132:135], v[172:175], v[104:107]
	v_mfma_f32_16x16x32_bf16 v[100:103], v[148:151], v[172:175], v[100:103]
	v_mfma_f32_16x16x32_bf16 v[88:91], v[132:135], v[180:183], v[88:91]
	v_mfma_f32_16x16x32_bf16 v[84:87], v[148:151], v[180:183], v[84:87]
	v_mfma_f32_16x16x32_bf16 v[72:75], v[132:135], v[188:191], v[72:75]
	v_mfma_f32_16x16x32_bf16 v[68:71], v[148:151], v[188:191], v[68:71]
	v_mfma_f32_16x16x32_bf16 v[144:147], v[140:143], v[168:171], v[144:147]
	v_mfma_f32_16x16x32_bf16 v[136:139], v[156:159], v[168:171], v[136:139]
	v_mfma_f32_16x16x32_bf16 v[104:107], v[140:143], v[176:179], v[104:107]
	v_mfma_f32_16x16x32_bf16 v[100:103], v[156:159], v[176:179], v[100:103]
	v_mfma_f32_16x16x32_bf16 v[88:91], v[140:143], v[184:187], v[88:91]
	v_mfma_f32_16x16x32_bf16 v[84:87], v[156:159], v[184:187], v[84:87]
	v_mfma_f32_16x16x32_bf16 v[72:75], v[140:143], v[192:195], v[72:75]
	v_mfma_f32_16x16x32_bf16 v[68:71], v[156:159], v[192:195], v[68:71]
	s_setprio 0
	s_barrier
	v_lshl_add_u64 v[212:213], s[30:31], 0, v[202:203]
	s_add_i32 m0, s41, 0x10000
	ds_read_b128 v[164:167], v253 offset:16384
	ds_read_b128 v[168:171], v253 offset:17408
	ds_read_b128 v[172:175], v253 offset:18432
	ds_read_b128 v[176:179], v253 offset:19456
	ds_read_b128 v[180:183], v253 offset:20480
	ds_read_b128 v[184:187], v253 offset:21504
	ds_read_b128 v[188:191], v253 offset:22528
	ds_read_b128 v[192:195], v253 offset:23552
	global_load_lds_dwordx4 v[212:213], off
	s_add_i32 m0, s41, 0x12000
	s_add_u32 s52, s30, 0x40000
	v_lshl_add_u64 v[214:215], s[30:31], 0, v[206:207]
	s_addc_u32 s53, s31, 0
	global_load_lds_dwordx4 v[214:215], off
	v_lshl_add_u64 v[216:217], s[52:53], 0, v[202:203]
	s_add_i32 m0, s41, 0x14000
	v_lshl_add_u64 v[218:219], s[34:35], 0, v[204:205]
	global_load_lds_dwordx4 v[216:217], off
	s_add_i32 m0, s41, 0x16000
	v_lshl_add_u64 v[216:217], s[52:53], 0, v[206:207]
	global_load_lds_dwordx4 v[216:217], off
	v_lshl_add_u64 v[216:217], s[34:35], 0, v[0:1]
	s_waitcnt vmcnt(6) lgkmcnt(0)
	s_barrier
	s_setprio 1
	v_mfma_f32_16x16x32_bf16 v[64:67], v[108:111], v[164:167], v[64:67]
	v_mfma_f32_16x16x32_bf16 v[60:63], v[124:127], v[164:167], v[60:63]
	v_mfma_f32_16x16x32_bf16 v[48:51], v[108:111], v[172:175], v[48:51]
	v_mfma_f32_16x16x32_bf16 v[44:47], v[124:127], v[172:175], v[44:47]
	v_mfma_f32_16x16x32_bf16 v[32:35], v[108:111], v[180:183], v[32:35]
	v_mfma_f32_16x16x32_bf16 v[28:31], v[124:127], v[180:183], v[28:31]
	v_mfma_f32_16x16x32_bf16 v[16:19], v[108:111], v[188:191], v[16:19]
	v_mfma_f32_16x16x32_bf16 v[12:15], v[124:127], v[188:191], v[12:15]
	v_mfma_f32_16x16x32_bf16 v[64:67], v[112:115], v[168:171], v[64:67]
	v_mfma_f32_16x16x32_bf16 v[60:63], v[128:131], v[168:171], v[60:63]
	v_mfma_f32_16x16x32_bf16 v[48:51], v[112:115], v[176:179], v[48:51]
	v_mfma_f32_16x16x32_bf16 v[44:47], v[128:131], v[176:179], v[44:47]
	v_mfma_f32_16x16x32_bf16 v[32:35], v[112:115], v[184:187], v[32:35]
	v_mfma_f32_16x16x32_bf16 v[28:31], v[128:131], v[184:187], v[28:31]
	v_mfma_f32_16x16x32_bf16 v[16:19], v[112:115], v[192:195], v[16:19]
	v_mfma_f32_16x16x32_bf16 v[12:15], v[128:131], v[192:195], v[12:15]
	s_setprio 0
	s_setprio 1
	v_mfma_f32_16x16x32_bf16 v[56:59], v[132:135], v[164:167], v[56:59]
	v_mfma_f32_16x16x32_bf16 v[52:55], v[148:151], v[164:167], v[52:55]
	v_mfma_f32_16x16x32_bf16 v[40:43], v[132:135], v[172:175], v[40:43]
	v_mfma_f32_16x16x32_bf16 v[36:39], v[148:151], v[172:175], v[36:39]
	v_mfma_f32_16x16x32_bf16 v[24:27], v[132:135], v[180:183], v[24:27]
	v_mfma_f32_16x16x32_bf16 v[20:23], v[148:151], v[180:183], v[20:23]
	v_mfma_f32_16x16x32_bf16 v[8:11], v[132:135], v[188:191], v[8:11]
	v_mfma_f32_16x16x32_bf16 v[4:7], v[148:151], v[188:191], v[4:7]
	v_mfma_f32_16x16x32_bf16 v[56:59], v[140:143], v[168:171], v[56:59]
	v_mfma_f32_16x16x32_bf16 v[52:55], v[156:159], v[168:171], v[52:55]
	v_mfma_f32_16x16x32_bf16 v[40:43], v[140:143], v[176:179], v[40:43]
	v_mfma_f32_16x16x32_bf16 v[36:39], v[156:159], v[176:179], v[36:39]
	v_mfma_f32_16x16x32_bf16 v[24:27], v[140:143], v[184:187], v[24:27]
	v_mfma_f32_16x16x32_bf16 v[20:23], v[156:159], v[184:187], v[20:23]
	v_mfma_f32_16x16x32_bf16 v[8:11], v[140:143], v[192:195], v[8:11]
	v_mfma_f32_16x16x32_bf16 v[4:7], v[156:159], v[192:195], v[4:7]
	s_setprio 0
	s_barrier
; #define PG8_STAGE(bufoff, gbase, voff) do { _Pragma("unroll") for (int _i = 0; _i < 2; ++_i) \
;         __builtin_amdgcn_global_load_lds((const unsigned*)((const char*)(gbase) + (voff)[_i]), (PG8_LAS unsigned*)(lds + (bufoff) + ldsw + _i * 8192), 16, 0, 0); } while (0)
; #define PG8_LDA(dst, b, h) do { _Pragma("unroll") for (int m = 0; m < 4; ++m) _Pragma("unroll") for (int k = 0; k < 2; ++k) dst[m][k] = *(const PG8_LAS bf16x8*)(lds + PG8_SA(b, h) + aoff + m * 2048 + k * 1024); } while (0)
; #define PG8_LDB(dst, b, h) do { _Pragma("unroll") for (int n = 0; n < 2; ++n) _Pragma("unroll") for (int k = 0; k < 2; ++k) dst[n][k] = *(const PG8_LAS bf16x8*)(lds + PG8_SB(b, h) + boff + n * 2048 + k * 1024); } while (0)
; #define PG8_MMA(ai, bj, At, Bt) do { __builtin_amdgcn_s_setprio(1); _Pragma("unroll") for (int m = 0; m < 4; ++m) _Pragma("unroll") for (int n = 0; n < 2; ++n) _Pragma("unroll") for (int k = 0; k < 2; ++k) \
;         acc[ai][bj][m][n] = __builtin_amdgcn_mfma_f32_16x16x32_bf16(Bt[n][k], At[m][k], acc[ai][bj][m][n], 0, 0, 0); __builtin_amdgcn_s_setprio(0); } while (0)
; #define PG8_WAIT_V(n) asm volatile("s_waitcnt vmcnt(" #n ")" ::: "memory")
; #define PG8_WAIT_L(n) asm volatile("s_waitcnt lgkmcnt(" #n ")" ::: "memory")
; #define PG8_BAR __builtin_amdgcn_s_barrier()
; #define PG8_SCHED __builtin_amdgcn_sched_barrier(0)
; template <class Epi, class Sched, bool ALIGN_EPI = false, bool SP2 = false>
; __device__ __forceinline__ void gemm_phase(PG8_LAS unsigned char* lds, const Gemm g, const Sched& S, const Epi& E) {
;     ...
;             PG8_LDB(B0, 1, 0); PG8_LDB(B1, 1, 1); PG8_SCHED; PG8_LDA(At, 1, 0); PG8_STAGE(PG8_SA(0, 1), a2 + hstep, voffA);
;             PG8_WAIT_V(8); PG8_WAIT_L(0); PG8_BAR; PG8_MMA(0, 0, At, B0); PG8_MMA(0, 1, At, B1); PG8_BAR; PG8_SCHED;
;             PG8_LDA(At, 1, 1); PG8_STAGE(PG8_SB(1, 0), b3, voffB); PG8_STAGE(PG8_SB(1, 1), b3 + hstep, voffB); PG8_STAGE(PG8_SA(1, 0), a3, voffA);
;             PG8_WAIT_V(8); PG8_WAIT_L(0); PG8_BAR; PG8_MMA(1, 0, At, B0); PG8_MMA(1, 1, At, B1); PG8_BAR; PG8_SCHED;
.Lkmid_1:
	ds_read_b128 v[108:111], v251 offset:32768
	ds_read_b128 v[112:115], v251 offset:33792
	ds_read_b128 v[124:127], v251 offset:34816
	ds_read_b128 v[128:131], v251 offset:35840
	ds_read_b128 v[132:135], v251 offset:49152
	ds_read_b128 v[140:143], v251 offset:50176
	ds_read_b128 v[148:151], v251 offset:51200
	ds_read_b128 v[156:159], v251 offset:52224
	s_mov_b32 m0, s42
	s_add_u32 s34, s34, 0x40000
	s_addc_u32 s35, s35, 0
	global_load_lds_dwordx4 v[216:217], off
	s_mov_b32 m0, s43
	v_lshl_add_u64 v[220:221], s[34:35], 0, v[0:1]
	global_load_lds_dwordx4 v[218:219], off
	s_mov_b32 m0, s46
	ds_read_b128 v[164:167], v253 offset:32768
	ds_read_b128 v[168:171], v253 offset:33792
	ds_read_b128 v[172:175], v253 offset:34816
	ds_read_b128 v[176:179], v253 offset:35840
	ds_read_b128 v[180:183], v253 offset:36864
	ds_read_b128 v[184:187], v253 offset:37888
	ds_read_b128 v[188:191], v253 offset:38912
	ds_read_b128 v[192:195], v253 offset:39936
	global_load_lds_dwordx4 v[220:221], off
	s_mov_b32 m0, s47
	v_lshl_add_u64 v[220:221], s[34:35], 0, v[204:205]
	global_load_lds_dwordx4 v[220:221], off
	s_waitcnt vmcnt(8) lgkmcnt(0)
	s_barrier
	s_setprio 1
	v_mfma_f32_16x16x32_bf16 v[160:163], v[108:111], v[164:167], v[160:163]
	v_mfma_f32_16x16x32_bf16 v[152:155], v[124:127], v[164:167], v[152:155]
	v_mfma_f32_16x16x32_bf16 v[120:123], v[108:111], v[172:175], v[120:123]
	v_mfma_f32_16x16x32_bf16 v[116:119], v[124:127], v[172:175], v[116:119]
	v_mfma_f32_16x16x32_bf16 v[96:99], v[108:111], v[180:183], v[96:99]
	v_mfma_f32_16x16x32_bf16 v[92:95], v[124:127], v[180:183], v[92:95]
	v_mfma_f32_16x16x32_bf16 v[80:83], v[108:111], v[188:191], v[80:83]
	v_mfma_f32_16x16x32_bf16 v[76:79], v[124:127], v[188:191], v[76:79]
	v_mfma_f32_16x16x32_bf16 v[160:163], v[112:115], v[168:171], v[160:163]
	v_mfma_f32_16x16x32_bf16 v[152:155], v[128:131], v[168:171], v[152:155]
	v_mfma_f32_16x16x32_bf16 v[120:123], v[112:115], v[176:179], v[120:123]
	v_mfma_f32_16x16x32_bf16 v[116:119], v[128:131], v[176:179], v[116:119]
	v_mfma_f32_16x16x32_bf16 v[96:99], v[112:115], v[184:187], v[96:99]
	v_mfma_f32_16x16x32_bf16 v[92:95], v[128:131], v[184:187], v[92:95]
	v_mfma_f32_16x16x32_bf16 v[80:83], v[112:115], v[192:195], v[80:83]
	v_mfma_f32_16x16x32_bf16 v[76:79], v[128:131], v[192:195], v[76:79]
	s_setprio 0
	s_setprio 1
	v_mfma_f32_16x16x32_bf16 v[144:147], v[132:135], v[164:167], v[144:147]
	v_mfma_f32_16x16x32_bf16 v[136:139], v[148:151], v[164:167], v[136:139]
	v_mfma_f32_16x16x32_bf16 v[104:107], v[132:135], v[172:175], v[104:107]
	v_mfma_f32_16x16x32_bf16 v[100:103], v[148:151], v[172:175], v[100:103]
	v_mfma_f32_16x16x32_bf16 v[88:91], v[132:135], v[180:183], v[88:91]
	v_mfma_f32_16x16x32_bf16 v[84:87], v[148:151], v[180:183], v[84:87]
	v_mfma_f32_16x16x32_bf16 v[72:75], v[132:135], v[188:191], v[72:75]
	v_mfma_f32_16x16x32_bf16 v[68:71], v[148:151], v[188:191], v[68:71]
	v_mfma_f32_16x16x32_bf16 v[144:147], v[140:143], v[168:171], v[144:147]
	v_mfma_f32_16x16x32_bf16 v[136:139], v[156:159], v[168:171], v[136:139]
	v_mfma_f32_16x16x32_bf16 v[104:107], v[140:143], v[176:179], v[104:107]
	v_mfma_f32_16x16x32_bf16 v[100:103], v[156:159], v[176:179], v[100:103]
	v_mfma_f32_16x16x32_bf16 v[88:91], v[140:143], v[184:187], v[88:91]
	v_mfma_f32_16x16x32_bf16 v[84:87], v[156:159], v[184:187], v[84:87]
	v_mfma_f32_16x16x32_bf16 v[72:75], v[140:143], v[192:195], v[72:75]
	v_mfma_f32_16x16x32_bf16 v[68:71], v[156:159], v[192:195], v[68:71]
	s_setprio 0
	s_barrier
	s_add_i32 m0, s41, 0x17f80
	ds_read_b128 v[164:167], v253 offset:49152
	ds_read_b128 v[168:171], v253 offset:50176
	ds_read_b128 v[172:175], v253 offset:51200
	ds_read_b128 v[176:179], v253 offset:52224
	ds_read_b128 v[180:183], v253 offset:53248
	ds_read_b128 v[184:187], v253 offset:54272
	ds_read_b128 v[188:191], v253 offset:55296
	ds_read_b128 v[192:195], v253 offset:56320
	global_load_lds_dwordx4 v[212:213], off offset:128
	s_add_i32 m0, s41, 0x19f80
	s_add_u32 s30, s30, 0x40080
	s_addc_u32 s31, s31, 0
	global_load_lds_dwordx4 v[214:215], off offset:128
	s_add_i32 m0, s41, 0x1c000
	v_lshl_add_u64 v[212:213], s[30:31], 0, v[202:203]
	global_load_lds_dwordx4 v[212:213], off
	s_add_i32 m0, s41, 0x1e000
	v_lshl_add_u64 v[212:213], s[30:31], 0, v[206:207]
	global_load_lds_dwordx4 v[212:213], off
	s_cmp_eq_u32 s45, 12
	s_cbranch_scc0 .Lks4_1
	s_add_i32 m0, s49, 0xffffff80
	s_nop 0
	global_load_lds_dwordx4 v[216:217], off offset:128
	s_add_i32 m0, s50, 0xffffff80
	s_nop 0
	global_load_lds_dwordx4 v[218:219], off offset:128
; #define PG8_STAGE(bufoff, gbase, voff) do { _Pragma("unroll") for (int _i = 0; _i < 2; ++_i) \
;         __builtin_amdgcn_global_load_lds((const unsigned*)((const char*)(gbase) + (voff)[_i]), (PG8_LAS unsigned*)(lds + (bufoff) + ldsw + _i * 8192), 16, 0, 0); } while (0)
; #define PG8_LDA(dst, b, h) do { _Pragma("unroll") for (int m = 0; m < 4; ++m) _Pragma("unroll") for (int k = 0; k < 2; ++k) dst[m][k] = *(const PG8_LAS bf16x8*)(lds + PG8_SA(b, h) + aoff + m * 2048 + k * 1024); } while (0)
; #define PG8_MMA(ai, bj, At, Bt) do { __builtin_amdgcn_s_setprio(1); _Pragma("unroll") for (int m = 0; m < 4; ++m) _Pragma("unroll") for (int n = 0; n < 2; ++n) _Pragma("unroll") for (int k = 0; k < 2; ++k) \
;         acc[ai][bj][m][n] = __builtin_amdgcn_mfma_f32_16x16x32_bf16(Bt[n][k], At[m][k], acc[ai][bj][m][n], 0, 0, 0); __builtin_amdgcn_s_setprio(0); } while (0)
; #define PG8_WAIT_V(n) asm volatile("s_waitcnt vmcnt(" #n ")" ::: "memory")
; #define PG8_WAIT_L(n) asm volatile("s_waitcnt lgkmcnt(" #n ")" ::: "memory")
; #define PG8_BAR __builtin_amdgcn_s_barrier()
; #define PG8_SCHED __builtin_amdgcn_sched_barrier(0)
; template <class Epi, class Sched, bool ALIGN_EPI = false, bool SP2 = false>
; __device__ __forceinline__ void gemm_phase(PG8_LAS unsigned char* lds, const Gemm g, const Sched& S, const Epi& E) {
;     ...
;         for (int t = 0; t < nt; t += 2) {
;     ...
;             PG8_LDA(At, 1, 1); PG8_STAGE(PG8_SB(1, 0), b3, voffB); PG8_STAGE(PG8_SB(1, 1), b3 + hstep, voffB); PG8_STAGE(PG8_SA(1, 0), a3, voffA);
;             PG8_WAIT_V(8); PG8_WAIT_L(0); PG8_BAR; PG8_MMA(1, 0, At, B0); PG8_MMA(1, 1, At, B1); PG8_BAR; PG8_SCHED;
.Lks4_1:
	s_add_u32 s28, s28, 0x100
	s_addc_u32 s29, s29, 0
	s_add_u32 s27, s27, 0x100
	s_addc_u32 s44, s44, 0
	s_waitcnt vmcnt(6) lgkmcnt(0)
	s_barrier
	s_setprio 1
	v_mfma_f32_16x16x32_bf16 v[64:67], v[108:111], v[164:167], v[64:67]
	v_mfma_f32_16x16x32_bf16 v[60:63], v[124:127], v[164:167], v[60:63]
	v_mfma_f32_16x16x32_bf16 v[48:51], v[108:111], v[172:175], v[48:51]
	v_mfma_f32_16x16x32_bf16 v[44:47], v[124:127], v[172:175], v[44:47]
	v_mfma_f32_16x16x32_bf16 v[32:35], v[108:111], v[180:183], v[32:35]
	v_mfma_f32_16x16x32_bf16 v[28:31], v[124:127], v[180:183], v[28:31]
	v_mfma_f32_16x16x32_bf16 v[16:19], v[108:111], v[188:191], v[16:19]
	v_mfma_f32_16x16x32_bf16 v[12:15], v[124:127], v[188:191], v[12:15]
	v_mfma_f32_16x16x32_bf16 v[64:67], v[112:115], v[168:171], v[64:67]
	v_mfma_f32_16x16x32_bf16 v[60:63], v[128:131], v[168:171], v[60:63]
	v_mfma_f32_16x16x32_bf16 v[48:51], v[112:115], v[176:179], v[48:51]
	v_mfma_f32_16x16x32_bf16 v[44:47], v[128:131], v[176:179], v[44:47]
	v_mfma_f32_16x16x32_bf16 v[32:35], v[112:115], v[184:187], v[32:35]
	v_mfma_f32_16x16x32_bf16 v[28:31], v[128:131], v[184:187], v[28:31]
	v_mfma_f32_16x16x32_bf16 v[16:19], v[112:115], v[192:195], v[16:19]
	v_mfma_f32_16x16x32_bf16 v[12:15], v[128:131], v[192:195], v[12:15]
	s_setprio 0
	s_setprio 1
	v_mfma_f32_16x16x32_bf16 v[56:59], v[132:135], v[164:167], v[56:59]
	v_mfma_f32_16x16x32_bf16 v[52:55], v[148:151], v[164:167], v[52:55]
	v_mfma_f32_16x16x32_bf16 v[40:43], v[132:135], v[172:175], v[40:43]
	v_mfma_f32_16x16x32_bf16 v[36:39], v[148:151], v[172:175], v[36:39]
	v_mfma_f32_16x16x32_bf16 v[24:27], v[132:135], v[180:183], v[24:27]
	v_mfma_f32_16x16x32_bf16 v[20:23], v[148:151], v[180:183], v[20:23]
	v_mfma_f32_16x16x32_bf16 v[8:11], v[132:135], v[188:191], v[8:11]
	v_mfma_f32_16x16x32_bf16 v[4:7], v[148:151], v[188:191], v[4:7]
	v_mfma_f32_16x16x32_bf16 v[56:59], v[140:143], v[168:171], v[56:59]
	v_mfma_f32_16x16x32_bf16 v[52:55], v[156:159], v[168:171], v[52:55]
	v_mfma_f32_16x16x32_bf16 v[40:43], v[140:143], v[176:179], v[40:43]
	v_mfma_f32_16x16x32_bf16 v[36:39], v[156:159], v[176:179], v[36:39]
	v_mfma_f32_16x16x32_bf16 v[24:27], v[140:143], v[184:187], v[24:27]
	v_mfma_f32_16x16x32_bf16 v[20:23], v[156:159], v[184:187], v[20:23]
	v_mfma_f32_16x16x32_bf16 v[8:11], v[140:143], v[192:195], v[8:11]
	v_mfma_f32_16x16x32_bf16 v[4:7], v[156:159], v[192:195], v[4:7]
	s_setprio 0
	s_barrier
	s_add_i32 s45, s45, 2
	s_cmp_gt_u32 s45, 13
	s_cbranch_scc0 .LBB0_329
	s_and_b64 vcc, exec, s[14:15]
	s_cbranch_vccz .LBB0_332
	s_barrier

; #define PG8_STAGE(bufoff, gbase, voff) do { _Pragma("unroll") for (int _i = 0; _i < 2; ++_i) \
;         __builtin_amdgcn_global_load_lds((const unsigned*)((const char*)(gbase) + (voff)[_i]), (PG8_LAS unsigned*)(lds + (bufoff) + ldsw + _i * 8192), 16, 0, 0); } while (0)
; #define PG8_LDA(dst, b, h) do { _Pragma("unroll") for (int m = 0; m < 4; ++m) _Pragma("unroll") for (int k = 0; k < 2; ++k) dst[m][k] = *(const PG8_LAS bf16x8*)(lds + PG8_SA(b, h) + aoff + m * 2048 + k * 1024); } while (0)
; #define PG8_LDB(dst, b, h) do { _Pragma("unroll") for (int n = 0; n < 2; ++n) _Pragma("unroll") for (int k = 0; k < 2; ++k) dst[n][k] = *(const PG8_LAS bf16x8*)(lds + PG8_SB(b, h) + boff + n * 2048 + k * 1024); } while (0)
; #define PG8_MMA(ai, bj, At, Bt) do { __builtin_amdgcn_s_setprio(1); _Pragma("unroll") for (int m = 0; m < 4; ++m) _Pragma("unroll") for (int n = 0; n < 2; ++n) _Pragma("unroll") for (int k = 0; k < 2; ++k) \
;         acc[ai][bj][m][n] = __builtin_amdgcn_mfma_f32_16x16x32_bf16(Bt[n][k], At[m][k], acc[ai][bj][m][n], 0, 0, 0); __builtin_amdgcn_s_setprio(0); } while (0)
; #define PG8_WAIT_V(n) asm volatile("s_waitcnt vmcnt(" #n ")" ::: "memory")
; #define PG8_WAIT_L(n) asm volatile("s_waitcnt lgkmcnt(" #n ")" ::: "memory")
; #define PG8_BAR __builtin_amdgcn_s_barrier()
; template <class Epi, class Sched, bool ALIGN_EPI = false, bool SP2 = false>
; __device__ __forceinline__ void gemm_phase(PG8_LAS unsigned char* lds, const Gemm g, const Sched& S, const Epi& E) {
;     ...
;             const char* a1 = cA + (size_t)(t + 1) * kstep;
;             const char* a2 = last ? nA : cA + (size_t)(t + 2) * kstep; const char* b2 = last ? nB : cB + (size_t)(t + 2) * kstep;
;             const char* a3 = a2 + kstep; const char* b3 = b2 + kstep;
;             if (last && has_next) S.a_ready(nxt);
;             if constexpr (SP2) {
;             PG8_LDB(B0, 0, 0); PG8_LDB(B1, 0, 1); PG8_SCHED; PG8_LDA(At, 0, 0); PG8_STAGE(PG8_SA(1, 1), a1 + hstep, voffA);
;             PG8_WAIT_V(8); PG8_WAIT_L(0); PG8_BAR; PG8_MMA(0, 0, At, B0); PG8_MMA(0, 1, At, B1); PG8_BAR; PG8_SCHED;
;             PG8_LDA(At, 0, 1); PG8_STAGE(PG8_SB(0, 0), b2, voffB); PG8_STAGE(PG8_SB(0, 1), b2 + hstep, voffB); PG8_STAGE(PG8_SA(0, 0), a2, voffA);
;             PG8_WAIT_V(8); PG8_WAIT_L(0); PG8_BAR; PG8_MMA(1, 0, At, B0); PG8_MMA(1, 1, At, B1); PG8_BAR; PG8_SCHED;
.LBB0_405:
	s_add_u32 s24, s8, 0xfffc0080
	s_addc_u32 s25, s9, -1
	s_cmp_eq_u32 s46, 12
	s_cselect_b32 s27, s7, s25
	s_cselect_b32 s26, s17, s24
	s_cselect_b32 s25, s19, s45
	s_cselect_b32 s24, s43, s44
	s_add_i32 m0, s41, 0xffffff80
	s_add_i32 s50, 0, 0x14000
	ds_read_b128 v[144:147], v164
	ds_read_b128 v[148:151], v164 offset:1024
	ds_read_b128 v[152:155], v164 offset:2048
	ds_read_b128 v[156:159], v164 offset:3072
	ds_read_b128 v[160:163], v164 offset:16384
	ds_read_b128 v[168:171], v164 offset:17408
	ds_read_b128 v[172:175], v164 offset:18432
	ds_read_b128 v[176:179], v164 offset:19456
	global_load_lds_dwordx4 v[220:221], off offset:128
	s_add_i32 m0, s42, 0xffffff80
	v_lshl_add_u64 v[198:199], s[8:9], 0, v[140:141]
	global_load_lds_dwordx4 v[222:223], off offset:128
	s_add_i32 m0, s37, 0xc000
	ds_read_b128 v[180:183], v166
	ds_read_b128 v[184:187], v166 offset:1024
	ds_read_b128 v[188:191], v166 offset:2048
	ds_read_b128 v[192:195], v166 offset:3072
	ds_read_b128 v[202:205], v166 offset:4096
	ds_read_b128 v[206:209], v166 offset:5120
	ds_read_b128 v[210:213], v166 offset:6144
	ds_read_b128 v[214:217], v166 offset:7168
	global_load_lds_dwordx4 v[198:199], off
	s_add_i32 m0, s37, 0xe000
	v_lshl_add_u64 v[198:199], s[8:9], 0, v[142:143]
	global_load_lds_dwordx4 v[198:199], off
	s_waitcnt vmcnt(8) lgkmcnt(0)
	s_barrier
	s_setprio 1
	v_mfma_f32_16x16x32_bf16 v[128:131], v[144:147], v[180:183], v[128:131]
	v_mfma_f32_16x16x32_bf16 v[120:123], v[152:155], v[180:183], v[120:123]
	v_mfma_f32_16x16x32_bf16 v[112:115], v[144:147], v[188:191], v[112:115]
	v_mfma_f32_16x16x32_bf16 v[104:107], v[152:155], v[188:191], v[104:107]
	v_mfma_f32_16x16x32_bf16 v[96:99], v[144:147], v[202:205], v[96:99]
	v_mfma_f32_16x16x32_bf16 v[88:91], v[152:155], v[202:205], v[88:91]
	v_mfma_f32_16x16x32_bf16 v[80:83], v[144:147], v[210:213], v[80:83]
	v_mfma_f32_16x16x32_bf16 v[72:75], v[152:155], v[210:213], v[72:75]
	v_mfma_f32_16x16x32_bf16 v[128:131], v[148:151], v[184:187], v[128:131]
	v_mfma_f32_16x16x32_bf16 v[120:123], v[156:159], v[184:187], v[120:123]
	v_mfma_f32_16x16x32_bf16 v[112:115], v[148:151], v[192:195], v[112:115]
	v_mfma_f32_16x16x32_bf16 v[104:107], v[156:159], v[192:195], v[104:107]
	v_mfma_f32_16x16x32_bf16 v[96:99], v[148:151], v[206:209], v[96:99]
	v_mfma_f32_16x16x32_bf16 v[88:91], v[156:159], v[206:209], v[88:91]
	v_mfma_f32_16x16x32_bf16 v[80:83], v[148:151], v[214:217], v[80:83]
	v_mfma_f32_16x16x32_bf16 v[72:75], v[156:159], v[214:217], v[72:75]
	s_setprio 0
	s_setprio 1
	v_mfma_f32_16x16x32_bf16 v[124:127], v[160:163], v[180:183], v[124:127]
	v_mfma_f32_16x16x32_bf16 v[116:119], v[172:175], v[180:183], v[116:119]
	v_mfma_f32_16x16x32_bf16 v[108:111], v[160:163], v[188:191], v[108:111]
	v_mfma_f32_16x16x32_bf16 v[100:103], v[172:175], v[188:191], v[100:103]
	v_mfma_f32_16x16x32_bf16 v[92:95], v[160:163], v[202:205], v[92:95]
	v_mfma_f32_16x16x32_bf16 v[84:87], v[172:175], v[202:205], v[84:87]
	v_mfma_f32_16x16x32_bf16 v[76:79], v[160:163], v[210:213], v[76:79]
	v_mfma_f32_16x16x32_bf16 v[68:71], v[172:175], v[210:213], v[68:71]
	v_mfma_f32_16x16x32_bf16 v[124:127], v[168:171], v[184:187], v[124:127]
	v_mfma_f32_16x16x32_bf16 v[116:119], v[176:179], v[184:187], v[116:119]
	v_mfma_f32_16x16x32_bf16 v[108:111], v[168:171], v[192:195], v[108:111]
	v_mfma_f32_16x16x32_bf16 v[100:103], v[176:179], v[192:195], v[100:103]
	v_mfma_f32_16x16x32_bf16 v[92:95], v[168:171], v[206:209], v[92:95]
	v_mfma_f32_16x16x32_bf16 v[84:87], v[176:179], v[206:209], v[84:87]
	v_mfma_f32_16x16x32_bf16 v[76:79], v[168:171], v[214:217], v[76:79]
	v_mfma_f32_16x16x32_bf16 v[68:71], v[176:179], v[214:217], v[68:71]
	s_setprio 0
	s_barrier
	v_lshl_add_u64 v[198:199], s[24:25], 0, v[134:135]
	s_add_i32 m0, s35, 0x10000
	ds_read_b128 v[180:183], v166 offset:16384
	ds_read_b128 v[184:187], v166 offset:17408
	ds_read_b128 v[188:191], v166 offset:18432
	ds_read_b128 v[192:195], v166 offset:19456
	ds_read_b128 v[202:205], v166 offset:20480
	ds_read_b128 v[206:209], v166 offset:21504
	ds_read_b128 v[210:213], v166 offset:22528
	ds_read_b128 v[214:217], v166 offset:23552
	global_load_lds_dwordx4 v[198:199], off
	s_add_i32 m0, s35, 0x12000
	s_add_u32 s48, s24, 0x40000
	v_lshl_add_u64 v[218:219], s[24:25], 0, v[0:1]
	s_addc_u32 s49, s25, 0
	global_load_lds_dwordx4 v[218:219], off
	v_lshl_add_u64 v[220:221], s[48:49], 0, v[134:135]
	s_add_i32 m0, s35, 0x14000
	v_lshl_add_u64 v[222:223], s[26:27], 0, v[132:133]
	global_load_lds_dwordx4 v[220:221], off
	s_add_i32 m0, s35, 0x16000
	v_lshl_add_u64 v[220:221], s[48:49], 0, v[0:1]
	global_load_lds_dwordx4 v[220:221], off
	v_lshl_add_u64 v[220:221], s[26:27], 0, v[136:137]
	s_waitcnt vmcnt(6) lgkmcnt(0)
	s_barrier
	s_setprio 1
	v_mfma_f32_16x16x32_bf16 v[64:67], v[144:147], v[180:183], v[64:67]
	v_mfma_f32_16x16x32_bf16 v[56:59], v[152:155], v[180:183], v[56:59]
	v_mfma_f32_16x16x32_bf16 v[48:51], v[144:147], v[188:191], v[48:51]
	v_mfma_f32_16x16x32_bf16 v[40:43], v[152:155], v[188:191], v[40:43]
	v_mfma_f32_16x16x32_bf16 v[32:35], v[144:147], v[202:205], v[32:35]
	v_mfma_f32_16x16x32_bf16 v[24:27], v[152:155], v[202:205], v[24:27]
	v_mfma_f32_16x16x32_bf16 v[16:19], v[144:147], v[210:213], v[16:19]
	v_mfma_f32_16x16x32_bf16 v[8:11], v[152:155], v[210:213], v[8:11]
	v_mfma_f32_16x16x32_bf16 v[64:67], v[148:151], v[184:187], v[64:67]
	v_mfma_f32_16x16x32_bf16 v[56:59], v[156:159], v[184:187], v[56:59]
	v_mfma_f32_16x16x32_bf16 v[48:51], v[148:151], v[192:195], v[48:51]
	v_mfma_f32_16x16x32_bf16 v[40:43], v[156:159], v[192:195], v[40:43]
	v_mfma_f32_16x16x32_bf16 v[32:35], v[148:151], v[206:209], v[32:35]
	v_mfma_f32_16x16x32_bf16 v[24:27], v[156:159], v[206:209], v[24:27]
	v_mfma_f32_16x16x32_bf16 v[16:19], v[148:151], v[214:217], v[16:19]
	v_mfma_f32_16x16x32_bf16 v[8:11], v[156:159], v[214:217], v[8:11]
	s_setprio 0
	s_setprio 1
	v_mfma_f32_16x16x32_bf16 v[60:63], v[160:163], v[180:183], v[60:63]
	v_mfma_f32_16x16x32_bf16 v[52:55], v[172:175], v[180:183], v[52:55]
	v_mfma_f32_16x16x32_bf16 v[44:47], v[160:163], v[188:191], v[44:47]
	v_mfma_f32_16x16x32_bf16 v[36:39], v[172:175], v[188:191], v[36:39]
	v_mfma_f32_16x16x32_bf16 v[28:31], v[160:163], v[202:205], v[28:31]
	v_mfma_f32_16x16x32_bf16 v[20:23], v[172:175], v[202:205], v[20:23]
	v_mfma_f32_16x16x32_bf16 v[12:15], v[160:163], v[210:213], v[12:15]
	v_mfma_f32_16x16x32_bf16 v[4:7], v[172:175], v[210:213], v[4:7]
	v_mfma_f32_16x16x32_bf16 v[60:63], v[168:171], v[184:187], v[60:63]
	v_mfma_f32_16x16x32_bf16 v[52:55], v[176:179], v[184:187], v[52:55]
	v_mfma_f32_16x16x32_bf16 v[44:47], v[168:171], v[192:195], v[44:47]
	v_mfma_f32_16x16x32_bf16 v[36:39], v[176:179], v[192:195], v[36:39]
	v_mfma_f32_16x16x32_bf16 v[28:31], v[168:171], v[206:209], v[28:31]
	v_mfma_f32_16x16x32_bf16 v[20:23], v[176:179], v[206:209], v[20:23]
	v_mfma_f32_16x16x32_bf16 v[12:15], v[168:171], v[214:217], v[12:15]
	v_mfma_f32_16x16x32_bf16 v[4:7], v[176:179], v[214:217], v[4:7]
	s_setprio 0
	s_barrier
; #define PG8_STAGE(bufoff, gbase, voff) do { _Pragma("unroll") for (int _i = 0; _i < 2; ++_i) \
;         __builtin_amdgcn_global_load_lds((const unsigned*)((const char*)(gbase) + (voff)[_i]), (PG8_LAS unsigned*)(lds + (bufoff) + ldsw + _i * 8192), 16, 0, 0); } while (0)
; #define PG8_LDA(dst, b, h) do { _Pragma("unroll") for (int m = 0; m < 4; ++m) _Pragma("unroll") for (int k = 0; k < 2; ++k) dst[m][k] = *(const PG8_LAS bf16x8*)(lds + PG8_SA(b, h) + aoff + m * 2048 + k * 1024); } while (0)
; #define PG8_LDB(dst, b, h) do { _Pragma("unroll") for (int n = 0; n < 2; ++n) _Pragma("unroll") for (int k = 0; k < 2; ++k) dst[n][k] = *(const PG8_LAS bf16x8*)(lds + PG8_SB(b, h) + boff + n * 2048 + k * 1024); } while (0)
; #define PG8_MMA(ai, bj, At, Bt) do { __builtin_amdgcn_s_setprio(1); _Pragma("unroll") for (int m = 0; m < 4; ++m) _Pragma("unroll") for (int n = 0; n < 2; ++n) _Pragma("unroll") for (int k = 0; k < 2; ++k) \
;         acc[ai][bj][m][n] = __builtin_amdgcn_mfma_f32_16x16x32_bf16(Bt[n][k], At[m][k], acc[ai][bj][m][n], 0, 0, 0); __builtin_amdgcn_s_setprio(0); } while (0)
; #define PG8_WAIT_V(n) asm volatile("s_waitcnt vmcnt(" #n ")" ::: "memory")
; #define PG8_WAIT_L(n) asm volatile("s_waitcnt lgkmcnt(" #n ")" ::: "memory")
; #define PG8_BAR __builtin_amdgcn_s_barrier()
; #define PG8_SCHED __builtin_amdgcn_sched_barrier(0)
; template <class Epi, class Sched, bool ALIGN_EPI = false, bool SP2 = false>
; __device__ __forceinline__ void gemm_phase(PG8_LAS unsigned char* lds, const Gemm g, const Sched& S, const Epi& E) {
;     ...
;             PG8_LDB(B0, 1, 0); PG8_LDB(B1, 1, 1); PG8_SCHED; PG8_LDA(At, 1, 0); PG8_STAGE(PG8_SA(0, 1), a2 + hstep, voffA);
;             PG8_WAIT_V(8); PG8_WAIT_L(0); PG8_BAR; PG8_MMA(0, 0, At, B0); PG8_MMA(0, 1, At, B1); PG8_BAR; PG8_SCHED;
;             PG8_LDA(At, 1, 1); PG8_STAGE(PG8_SB(1, 0), b3, voffB); PG8_STAGE(PG8_SB(1, 1), b3 + hstep, voffB); PG8_STAGE(PG8_SA(1, 0), a3, voffA);
;             PG8_WAIT_V(8); PG8_WAIT_L(0); PG8_BAR; PG8_MMA(1, 0, At, B0); PG8_MMA(1, 1, At, B1); PG8_BAR; PG8_SCHED;
.Lkmid_2:
	ds_read_b128 v[144:147], v164 offset:32768
	ds_read_b128 v[148:151], v164 offset:33792
	ds_read_b128 v[152:155], v164 offset:34816
	ds_read_b128 v[156:159], v164 offset:35840
	ds_read_b128 v[160:163], v164 offset:49152
	ds_read_b128 v[168:171], v164 offset:50176
	ds_read_b128 v[172:175], v164 offset:51200
	ds_read_b128 v[176:179], v164 offset:52224
	s_mov_b32 m0, s37
	s_add_u32 s26, s26, 0x40000
	s_addc_u32 s27, s27, 0
	global_load_lds_dwordx4 v[220:221], off
	s_mov_b32 m0, s38
	v_lshl_add_u64 v[224:225], s[26:27], 0, v[136:137]
	global_load_lds_dwordx4 v[222:223], off
	s_mov_b32 m0, s39
	ds_read_b128 v[180:183], v166 offset:32768
	ds_read_b128 v[184:187], v166 offset:33792
	ds_read_b128 v[188:191], v166 offset:34816
	ds_read_b128 v[192:195], v166 offset:35840
	ds_read_b128 v[202:205], v166 offset:36864
	ds_read_b128 v[206:209], v166 offset:37888
	ds_read_b128 v[210:213], v166 offset:38912
	ds_read_b128 v[214:217], v166 offset:39936
	global_load_lds_dwordx4 v[224:225], off
	s_mov_b32 m0, s40
	v_lshl_add_u64 v[224:225], s[26:27], 0, v[132:133]
	global_load_lds_dwordx4 v[224:225], off
	s_waitcnt vmcnt(8) lgkmcnt(0)
	s_barrier
	s_setprio 1
	v_mfma_f32_16x16x32_bf16 v[128:131], v[144:147], v[180:183], v[128:131]
	v_mfma_f32_16x16x32_bf16 v[120:123], v[152:155], v[180:183], v[120:123]
	v_mfma_f32_16x16x32_bf16 v[112:115], v[144:147], v[188:191], v[112:115]
	v_mfma_f32_16x16x32_bf16 v[104:107], v[152:155], v[188:191], v[104:107]
	v_mfma_f32_16x16x32_bf16 v[96:99], v[144:147], v[202:205], v[96:99]
	v_mfma_f32_16x16x32_bf16 v[88:91], v[152:155], v[202:205], v[88:91]
	v_mfma_f32_16x16x32_bf16 v[80:83], v[144:147], v[210:213], v[80:83]
	v_mfma_f32_16x16x32_bf16 v[72:75], v[152:155], v[210:213], v[72:75]
	v_mfma_f32_16x16x32_bf16 v[128:131], v[148:151], v[184:187], v[128:131]
	v_mfma_f32_16x16x32_bf16 v[120:123], v[156:159], v[184:187], v[120:123]
	v_mfma_f32_16x16x32_bf16 v[112:115], v[148:151], v[192:195], v[112:115]
	v_mfma_f32_16x16x32_bf16 v[104:107], v[156:159], v[192:195], v[104:107]
	v_mfma_f32_16x16x32_bf16 v[96:99], v[148:151], v[206:209], v[96:99]
	v_mfma_f32_16x16x32_bf16 v[88:91], v[156:159], v[206:209], v[88:91]
	v_mfma_f32_16x16x32_bf16 v[80:83], v[148:151], v[214:217], v[80:83]
	v_mfma_f32_16x16x32_bf16 v[72:75], v[156:159], v[214:217], v[72:75]
	s_setprio 0
	s_setprio 1
	v_mfma_f32_16x16x32_bf16 v[124:127], v[160:163], v[180:183], v[124:127]
	v_mfma_f32_16x16x32_bf16 v[116:119], v[172:175], v[180:183], v[116:119]
	v_mfma_f32_16x16x32_bf16 v[108:111], v[160:163], v[188:191], v[108:111]
	v_mfma_f32_16x16x32_bf16 v[100:103], v[172:175], v[188:191], v[100:103]
	v_mfma_f32_16x16x32_bf16 v[92:95], v[160:163], v[202:205], v[92:95]
	v_mfma_f32_16x16x32_bf16 v[84:87], v[172:175], v[202:205], v[84:87]
	v_mfma_f32_16x16x32_bf16 v[76:79], v[160:163], v[210:213], v[76:79]
	v_mfma_f32_16x16x32_bf16 v[68:71], v[172:175], v[210:213], v[68:71]
	v_mfma_f32_16x16x32_bf16 v[124:127], v[168:171], v[184:187], v[124:127]
	v_mfma_f32_16x16x32_bf16 v[116:119], v[176:179], v[184:187], v[116:119]
	v_mfma_f32_16x16x32_bf16 v[108:111], v[168:171], v[192:195], v[108:111]
	v_mfma_f32_16x16x32_bf16 v[100:103], v[176:179], v[192:195], v[100:103]
	v_mfma_f32_16x16x32_bf16 v[92:95], v[168:171], v[206:209], v[92:95]
	v_mfma_f32_16x16x32_bf16 v[84:87], v[176:179], v[206:209], v[84:87]
	v_mfma_f32_16x16x32_bf16 v[76:79], v[168:171], v[214:217], v[76:79]
	v_mfma_f32_16x16x32_bf16 v[68:71], v[176:179], v[214:217], v[68:71]
	s_setprio 0
	s_barrier
	s_add_i32 m0, s35, 0x17f80
	ds_read_b128 v[180:183], v166 offset:49152
	ds_read_b128 v[184:187], v166 offset:50176
	ds_read_b128 v[188:191], v166 offset:51200
	ds_read_b128 v[192:195], v166 offset:52224
	ds_read_b128 v[202:205], v166 offset:53248
	ds_read_b128 v[206:209], v166 offset:54272
	ds_read_b128 v[210:213], v166 offset:55296
	ds_read_b128 v[214:217], v166 offset:56320
	global_load_lds_dwordx4 v[198:199], off offset:128
	s_add_i32 m0, s35, 0x19f80
	s_add_u32 s24, s24, 0x40080
	s_addc_u32 s25, s25, 0
	global_load_lds_dwordx4 v[218:219], off offset:128
	s_add_i32 m0, s35, 0x1c000
	v_lshl_add_u64 v[198:199], s[24:25], 0, v[134:135]
	global_load_lds_dwordx4 v[198:199], off
	s_add_i32 m0, s35, 0x1e000
	v_lshl_add_u64 v[198:199], s[24:25], 0, v[0:1]
	global_load_lds_dwordx4 v[198:199], off
	s_cmp_eq_u32 s46, 12
	s_cbranch_scc0 .Lks4_2
	s_add_i32 m0, s41, 0xffffff80
	s_nop 0
	global_load_lds_dwordx4 v[220:221], off offset:128
	s_add_i32 m0, s42, 0xffffff80
	s_nop 0
	global_load_lds_dwordx4 v[222:223], off offset:128
; #define PG8_STAGE(bufoff, gbase, voff) do { _Pragma("unroll") for (int _i = 0; _i < 2; ++_i) \
;         __builtin_amdgcn_global_load_lds((const unsigned*)((const char*)(gbase) + (voff)[_i]), (PG8_LAS unsigned*)(lds + (bufoff) + ldsw + _i * 8192), 16, 0, 0); } while (0)
; #define PG8_LDA(dst, b, h) do { _Pragma("unroll") for (int m = 0; m < 4; ++m) _Pragma("unroll") for (int k = 0; k < 2; ++k) dst[m][k] = *(const PG8_LAS bf16x8*)(lds + PG8_SA(b, h) + aoff + m * 2048 + k * 1024); } while (0)
; #define PG8_MMA(ai, bj, At, Bt) do { __builtin_amdgcn_s_setprio(1); _Pragma("unroll") for (int m = 0; m < 4; ++m) _Pragma("unroll") for (int n = 0; n < 2; ++n) _Pragma("unroll") for (int k = 0; k < 2; ++k) \
;         acc[ai][bj][m][n] = __builtin_amdgcn_mfma_f32_16x16x32_bf16(Bt[n][k], At[m][k], acc[ai][bj][m][n], 0, 0, 0); __builtin_amdgcn_s_setprio(0); } while (0)
; #define PG8_WAIT_V(n) asm volatile("s_waitcnt vmcnt(" #n ")" ::: "memory")
; #define PG8_WAIT_L(n) asm volatile("s_waitcnt lgkmcnt(" #n ")" ::: "memory")
; #define PG8_BAR __builtin_amdgcn_s_barrier()
; #define PG8_SCHED __builtin_amdgcn_sched_barrier(0)
; template <class Epi, class Sched, bool ALIGN_EPI = false, bool SP2 = false>
; __device__ __forceinline__ void gemm_phase(PG8_LAS unsigned char* lds, const Gemm g, const Sched& S, const Epi& E) {
;     ...
;         for (int t = 0; t < nt; t += 2) {
;             const bool last = (t == nt - 2);
;             const char* a1 = cA + (size_t)(t + 1) * kstep;
;             const char* a2 = last ? nA : cA + (size_t)(t + 2) * kstep; const char* b2 = last ? nB : cB + (size_t)(t + 2) * kstep;
;             const char* a3 = a2 + kstep; const char* b3 = b2 + kstep;
;             if (last && has_next) S.a_ready(nxt);
;     ...
;             PG8_LDA(At, 1, 1); PG8_STAGE(PG8_SB(1, 0), b3, voffB); PG8_STAGE(PG8_SB(1, 1), b3 + hstep, voffB); PG8_STAGE(PG8_SA(1, 0), a3, voffA);
;             PG8_WAIT_V(8); PG8_WAIT_L(0); PG8_BAR; PG8_MMA(1, 0, At, B0); PG8_MMA(1, 1, At, B1); PG8_BAR; PG8_SCHED;
.Lks4_2:
	s_add_u32 s8, s8, 0x100
	s_addc_u32 s9, s9, 0
	s_add_u32 s44, s44, 0x100
	s_addc_u32 s45, s45, 0
	s_waitcnt vmcnt(6) lgkmcnt(0)
	s_barrier
	s_setprio 1
	v_mfma_f32_16x16x32_bf16 v[64:67], v[144:147], v[180:183], v[64:67]
	v_mfma_f32_16x16x32_bf16 v[56:59], v[152:155], v[180:183], v[56:59]
	v_mfma_f32_16x16x32_bf16 v[48:51], v[144:147], v[188:191], v[48:51]
	v_mfma_f32_16x16x32_bf16 v[40:43], v[152:155], v[188:191], v[40:43]
	v_mfma_f32_16x16x32_bf16 v[32:35], v[144:147], v[202:205], v[32:35]
	v_mfma_f32_16x16x32_bf16 v[24:27], v[152:155], v[202:205], v[24:27]
	v_mfma_f32_16x16x32_bf16 v[16:19], v[144:147], v[210:213], v[16:19]
	v_mfma_f32_16x16x32_bf16 v[8:11], v[152:155], v[210:213], v[8:11]
	v_mfma_f32_16x16x32_bf16 v[64:67], v[148:151], v[184:187], v[64:67]
	v_mfma_f32_16x16x32_bf16 v[56:59], v[156:159], v[184:187], v[56:59]
	v_mfma_f32_16x16x32_bf16 v[48:51], v[148:151], v[192:195], v[48:51]
	v_mfma_f32_16x16x32_bf16 v[40:43], v[156:159], v[192:195], v[40:43]
	v_mfma_f32_16x16x32_bf16 v[32:35], v[148:151], v[206:209], v[32:35]
	v_mfma_f32_16x16x32_bf16 v[24:27], v[156:159], v[206:209], v[24:27]
	v_mfma_f32_16x16x32_bf16 v[16:19], v[148:151], v[214:217], v[16:19]
	v_mfma_f32_16x16x32_bf16 v[8:11], v[156:159], v[214:217], v[8:11]
	s_setprio 0
	s_setprio 1
	v_mfma_f32_16x16x32_bf16 v[60:63], v[160:163], v[180:183], v[60:63]
	v_mfma_f32_16x16x32_bf16 v[52:55], v[172:175], v[180:183], v[52:55]
	v_mfma_f32_16x16x32_bf16 v[44:47], v[160:163], v[188:191], v[44:47]
	v_mfma_f32_16x16x32_bf16 v[36:39], v[172:175], v[188:191], v[36:39]
	v_mfma_f32_16x16x32_bf16 v[28:31], v[160:163], v[202:205], v[28:31]
	v_mfma_f32_16x16x32_bf16 v[20:23], v[172:175], v[202:205], v[20:23]
	v_mfma_f32_16x16x32_bf16 v[12:15], v[160:163], v[210:213], v[12:15]
	v_mfma_f32_16x16x32_bf16 v[4:7], v[172:175], v[210:213], v[4:7]
	v_mfma_f32_16x16x32_bf16 v[60:63], v[168:171], v[184:187], v[60:63]
	v_mfma_f32_16x16x32_bf16 v[52:55], v[176:179], v[184:187], v[52:55]
	v_mfma_f32_16x16x32_bf16 v[44:47], v[168:171], v[192:195], v[44:47]
	v_mfma_f32_16x16x32_bf16 v[36:39], v[176:179], v[192:195], v[36:39]
	v_mfma_f32_16x16x32_bf16 v[28:31], v[168:171], v[206:209], v[28:31]
	v_mfma_f32_16x16x32_bf16 v[20:23], v[176:179], v[206:209], v[20:23]
	v_mfma_f32_16x16x32_bf16 v[12:15], v[168:171], v[214:217], v[12:15]
	v_mfma_f32_16x16x32_bf16 v[4:7], v[176:179], v[214:217], v[4:7]
	s_setprio 0
	s_barrier
	s_add_i32 s46, s46, 2
	s_cmp_gt_u32 s46, 13
	s_cbranch_scc0 .LBB0_405
	s_and_b64 vcc, exec, s[14:15]
	s_cbranch_vccz .LBB0_408
	s_barrier

; #define PG8_STAGE(bufoff, gbase, voff) do { _Pragma("unroll") for (int _i = 0; _i < 2; ++_i) \
;         __builtin_amdgcn_global_load_lds((const unsigned*)((const char*)(gbase) + (voff)[_i]), (PG8_LAS unsigned*)(lds + (bufoff) + ldsw + _i * 8192), 16, 0, 0); } while (0)
; #define PG8_LDA(dst, b, h) do { _Pragma("unroll") for (int m = 0; m < 4; ++m) _Pragma("unroll") for (int k = 0; k < 2; ++k) dst[m][k] = *(const PG8_LAS bf16x8*)(lds + PG8_SA(b, h) + aoff + m * 2048 + k * 1024); } while (0)
; #define PG8_LDB(dst, b, h) do { _Pragma("unroll") for (int n = 0; n < 2; ++n) _Pragma("unroll") for (int k = 0; k < 2; ++k) dst[n][k] = *(const PG8_LAS bf16x8*)(lds + PG8_SB(b, h) + boff + n * 2048 + k * 1024); } while (0)
; #define PG8_MMA(ai, bj, At, Bt) do { __builtin_amdgcn_s_setprio(1); _Pragma("unroll") for (int m = 0; m < 4; ++m) _Pragma("unroll") for (int n = 0; n < 2; ++n) _Pragma("unroll") for (int k = 0; k < 2; ++k) \
;         acc[ai][bj][m][n] = __builtin_amdgcn_mfma_f32_16x16x32_bf16(Bt[n][k], At[m][k], acc[ai][bj][m][n], 0, 0, 0); __builtin_amdgcn_s_setprio(0); } while (0)
; #define PG8_WAIT_V(n) asm volatile("s_waitcnt vmcnt(" #n ")" ::: "memory")
; #define PG8_WAIT_L(n) asm volatile("s_waitcnt lgkmcnt(" #n ")" ::: "memory")
; template <class Epi, class Sched, bool ALIGN_EPI = false, bool SP2 = false>
; __device__ __forceinline__ void gemm_phase(PG8_LAS unsigned char* lds, const Gemm g, const Sched& S, const Epi& E) {
;     ...
;             const bool last = (t == nt - 2);
;             const char* a1 = cA + (size_t)(t + 1) * kstep;
;             const char* a2 = last ? nA : cA + (size_t)(t + 2) * kstep; const char* b2 = last ? nB : cB + (size_t)(t + 2) * kstep;
;             const char* a3 = a2 + kstep; const char* b3 = b2 + kstep;
;             if (last && has_next) S.a_ready(nxt);
;             if constexpr (SP2) {
;             PG8_LDB(B0, 0, 0); PG8_LDB(B1, 0, 1); PG8_SCHED; PG8_LDA(At, 0, 0); PG8_STAGE(PG8_SA(1, 1), a1 + hstep, voffA);
;             PG8_WAIT_V(8); PG8_WAIT_L(0); PG8_BAR; PG8_MMA(0, 0, At, B0); PG8_MMA(0, 1, At, B1); PG8_BAR; PG8_SCHED;
;             PG8_LDA(At, 0, 1); PG8_STAGE(PG8_SB(0, 0), b2, voffB); PG8_STAGE(PG8_SB(0, 1), b2 + hstep, voffB); PG8_STAGE(PG8_SA(0, 0), a2, voffA);
;             PG8_WAIT_V(8); PG8_WAIT_L(0); PG8_BAR; PG8_MMA(1, 0, At, B0); PG8_MMA(1, 1, At, B1); PG8_BAR; PG8_SCHED;
.LBB0_480:
	s_add_u32 s8, s26, 0x100
	s_addc_u32 s9, s27, 0
	s_cmp_eq_u32 s53, 40
	s_cselect_b32 s31, s23, s9
	s_cselect_b32 s30, s22, s8
	s_cselect_b32 s29, s25, s45
	s_cselect_b32 s28, s24, s44
	s_add_i32 m0, s47, 0xffffff80
	ds_read_b128 v[68:71], v234
	ds_read_b128 v[80:83], v234 offset:1024
	ds_read_b128 v[92:95], v234 offset:2048
	ds_read_b128 v[100:103], v234 offset:3072
	ds_read_b128 v[112:115], v234 offset:16384
	ds_read_b128 v[120:123], v234 offset:17408
	ds_read_b128 v[132:135], v234 offset:18432
	ds_read_b128 v[144:147], v234 offset:19456
	global_load_lds_dwordx4 v[214:215], off offset:128
	s_add_i32 m0, s48, 0xffffff80
	v_lshl_add_u64 v[198:199], s[26:27], 0, v[204:205]
	global_load_lds_dwordx4 v[216:217], off offset:128
	s_add_i32 m0, s40, 0xc000
	ds_read_b128 v[156:159], v236
	ds_read_b128 v[168:171], v236 offset:1024
	ds_read_b128 v[172:175], v236 offset:2048
	ds_read_b128 v[176:179], v236 offset:3072
	ds_read_b128 v[180:183], v236 offset:4096
	ds_read_b128 v[184:187], v236 offset:5120
	ds_read_b128 v[188:191], v236 offset:6144
	ds_read_b128 v[208:211], v236 offset:7168
	global_load_lds_dwordx4 v[198:199], off
	s_add_i32 m0, s40, 0xe000
	v_lshl_add_u64 v[198:199], s[26:27], 0, v[206:207]
	global_load_lds_dwordx4 v[198:199], off
	s_waitcnt vmcnt(8) lgkmcnt(0)
	s_barrier
	s_setprio 1
	v_mfma_f32_16x16x32_bf16 v[164:167], v[68:71], v[156:159], v[164:167]
	v_mfma_f32_16x16x32_bf16 v[160:163], v[92:95], v[156:159], v[160:163]
	v_mfma_f32_16x16x32_bf16 v[140:143], v[68:71], v[172:175], v[140:143]
	v_mfma_f32_16x16x32_bf16 v[136:139], v[92:95], v[172:175], v[136:139]
	v_mfma_f32_16x16x32_bf16 v[116:119], v[68:71], v[180:183], v[116:119]
	v_mfma_f32_16x16x32_bf16 v[108:111], v[92:95], v[180:183], v[108:111]
	v_mfma_f32_16x16x32_bf16 v[88:91], v[68:71], v[188:191], v[88:91]
	v_mfma_f32_16x16x32_bf16 v[84:87], v[92:95], v[188:191], v[84:87]
	v_mfma_f32_16x16x32_bf16 v[164:167], v[80:83], v[168:171], v[164:167]
	v_mfma_f32_16x16x32_bf16 v[160:163], v[100:103], v[168:171], v[160:163]
	v_mfma_f32_16x16x32_bf16 v[140:143], v[80:83], v[176:179], v[140:143]
	v_mfma_f32_16x16x32_bf16 v[136:139], v[100:103], v[176:179], v[136:139]
	v_mfma_f32_16x16x32_bf16 v[116:119], v[80:83], v[184:187], v[116:119]
	v_mfma_f32_16x16x32_bf16 v[108:111], v[100:103], v[184:187], v[108:111]
	v_mfma_f32_16x16x32_bf16 v[88:91], v[80:83], v[208:211], v[88:91]
	v_mfma_f32_16x16x32_bf16 v[84:87], v[100:103], v[208:211], v[84:87]
	s_setprio 0
	s_setprio 1
	v_mfma_f32_16x16x32_bf16 v[152:155], v[112:115], v[156:159], v[152:155]
	v_mfma_f32_16x16x32_bf16 v[148:151], v[132:135], v[156:159], v[148:151]
	v_mfma_f32_16x16x32_bf16 v[128:131], v[112:115], v[172:175], v[128:131]
	v_mfma_f32_16x16x32_bf16 v[124:127], v[132:135], v[172:175], v[124:127]
	v_mfma_f32_16x16x32_bf16 v[104:107], v[112:115], v[180:183], v[104:107]
	v_mfma_f32_16x16x32_bf16 v[96:99], v[132:135], v[180:183], v[96:99]
	v_mfma_f32_16x16x32_bf16 v[76:79], v[112:115], v[188:191], v[76:79]
	v_mfma_f32_16x16x32_bf16 v[72:75], v[132:135], v[188:191], v[72:75]
	v_mfma_f32_16x16x32_bf16 v[152:155], v[120:123], v[168:171], v[152:155]
	v_mfma_f32_16x16x32_bf16 v[148:151], v[144:147], v[168:171], v[148:151]
	v_mfma_f32_16x16x32_bf16 v[128:131], v[120:123], v[176:179], v[128:131]
	v_mfma_f32_16x16x32_bf16 v[124:127], v[144:147], v[176:179], v[124:127]
	v_mfma_f32_16x16x32_bf16 v[104:107], v[120:123], v[184:187], v[104:107]
	v_mfma_f32_16x16x32_bf16 v[96:99], v[144:147], v[184:187], v[96:99]
	v_mfma_f32_16x16x32_bf16 v[76:79], v[120:123], v[208:211], v[76:79]
	v_mfma_f32_16x16x32_bf16 v[72:75], v[144:147], v[208:211], v[72:75]
	s_setprio 0
	s_barrier
	v_lshl_add_u64 v[198:199], s[28:29], 0, v[192:193]
	s_add_i32 m0, s39, 0x10000
	ds_read_b128 v[156:159], v236 offset:16384
	ds_read_b128 v[168:171], v236 offset:17408
	ds_read_b128 v[172:175], v236 offset:18432
	ds_read_b128 v[176:179], v236 offset:19456
	ds_read_b128 v[180:183], v236 offset:20480
	ds_read_b128 v[184:187], v236 offset:21504
	ds_read_b128 v[188:191], v236 offset:22528
	ds_read_b128 v[208:211], v236 offset:23552
	global_load_lds_dwordx4 v[198:199], off
	s_add_i32 m0, s39, 0x12000
	s_add_u32 s26, s28, 0xb0000
	v_lshl_add_u64 v[212:213], s[28:29], 0, v[202:203]
	s_addc_u32 s27, s29, 0
	global_load_lds_dwordx4 v[212:213], off
	v_lshl_add_u64 v[214:215], s[26:27], 0, v[192:193]
	s_add_i32 m0, s39, 0x14000
	v_lshl_add_u64 v[216:217], s[30:31], 0, v[194:195]
	global_load_lds_dwordx4 v[214:215], off
	s_add_i32 m0, s39, 0x16000
	v_lshl_add_u64 v[214:215], s[26:27], 0, v[202:203]
	global_load_lds_dwordx4 v[214:215], off
	v_lshl_add_u64 v[214:215], s[30:31], 0, v[0:1]
	s_waitcnt vmcnt(6) lgkmcnt(0)
	s_barrier
	s_setprio 1
	v_mfma_f32_16x16x32_bf16 v[64:67], v[68:71], v[156:159], v[64:67]
	v_mfma_f32_16x16x32_bf16 v[60:63], v[92:95], v[156:159], v[60:63]
	v_mfma_f32_16x16x32_bf16 v[48:51], v[68:71], v[172:175], v[48:51]
	v_mfma_f32_16x16x32_bf16 v[44:47], v[92:95], v[172:175], v[44:47]
	v_mfma_f32_16x16x32_bf16 v[32:35], v[68:71], v[180:183], v[32:35]
	v_mfma_f32_16x16x32_bf16 v[28:31], v[92:95], v[180:183], v[28:31]
	v_mfma_f32_16x16x32_bf16 v[16:19], v[68:71], v[188:191], v[16:19]
	v_mfma_f32_16x16x32_bf16 v[12:15], v[92:95], v[188:191], v[12:15]
	v_mfma_f32_16x16x32_bf16 v[64:67], v[80:83], v[168:171], v[64:67]
	v_mfma_f32_16x16x32_bf16 v[60:63], v[100:103], v[168:171], v[60:63]
	v_mfma_f32_16x16x32_bf16 v[48:51], v[80:83], v[176:179], v[48:51]
	v_mfma_f32_16x16x32_bf16 v[44:47], v[100:103], v[176:179], v[44:47]
	v_mfma_f32_16x16x32_bf16 v[32:35], v[80:83], v[184:187], v[32:35]
	v_mfma_f32_16x16x32_bf16 v[28:31], v[100:103], v[184:187], v[28:31]
	v_mfma_f32_16x16x32_bf16 v[16:19], v[80:83], v[208:211], v[16:19]
	v_mfma_f32_16x16x32_bf16 v[12:15], v[100:103], v[208:211], v[12:15]
	s_setprio 0
	s_setprio 1
	v_mfma_f32_16x16x32_bf16 v[56:59], v[112:115], v[156:159], v[56:59]
	v_mfma_f32_16x16x32_bf16 v[52:55], v[132:135], v[156:159], v[52:55]
	v_mfma_f32_16x16x32_bf16 v[40:43], v[112:115], v[172:175], v[40:43]
	v_mfma_f32_16x16x32_bf16 v[36:39], v[132:135], v[172:175], v[36:39]
	v_mfma_f32_16x16x32_bf16 v[24:27], v[112:115], v[180:183], v[24:27]
	v_mfma_f32_16x16x32_bf16 v[20:23], v[132:135], v[180:183], v[20:23]
	v_mfma_f32_16x16x32_bf16 v[8:11], v[112:115], v[188:191], v[8:11]
	v_mfma_f32_16x16x32_bf16 v[4:7], v[132:135], v[188:191], v[4:7]
	v_mfma_f32_16x16x32_bf16 v[56:59], v[120:123], v[168:171], v[56:59]
	v_mfma_f32_16x16x32_bf16 v[52:55], v[144:147], v[168:171], v[52:55]
	v_mfma_f32_16x16x32_bf16 v[40:43], v[120:123], v[176:179], v[40:43]
	v_mfma_f32_16x16x32_bf16 v[36:39], v[144:147], v[176:179], v[36:39]
	v_mfma_f32_16x16x32_bf16 v[24:27], v[120:123], v[184:187], v[24:27]
	v_mfma_f32_16x16x32_bf16 v[20:23], v[144:147], v[184:187], v[20:23]
	v_mfma_f32_16x16x32_bf16 v[8:11], v[120:123], v[208:211], v[8:11]
	v_mfma_f32_16x16x32_bf16 v[4:7], v[144:147], v[208:211], v[4:7]
	s_setprio 0
	s_barrier
; #define PG8_STAGE(bufoff, gbase, voff) do { _Pragma("unroll") for (int _i = 0; _i < 2; ++_i) \
;         __builtin_amdgcn_global_load_lds((const unsigned*)((const char*)(gbase) + (voff)[_i]), (PG8_LAS unsigned*)(lds + (bufoff) + ldsw + _i * 8192), 16, 0, 0); } while (0)
; #define PG8_LDA(dst, b, h) do { _Pragma("unroll") for (int m = 0; m < 4; ++m) _Pragma("unroll") for (int k = 0; k < 2; ++k) dst[m][k] = *(const PG8_LAS bf16x8*)(lds + PG8_SA(b, h) + aoff + m * 2048 + k * 1024); } while (0)
; #define PG8_LDB(dst, b, h) do { _Pragma("unroll") for (int n = 0; n < 2; ++n) _Pragma("unroll") for (int k = 0; k < 2; ++k) dst[n][k] = *(const PG8_LAS bf16x8*)(lds + PG8_SB(b, h) + boff + n * 2048 + k * 1024); } while (0)
; #define PG8_MMA(ai, bj, At, Bt) do { __builtin_amdgcn_s_setprio(1); _Pragma("unroll") for (int m = 0; m < 4; ++m) _Pragma("unroll") for (int n = 0; n < 2; ++n) _Pragma("unroll") for (int k = 0; k < 2; ++k) \
;         acc[ai][bj][m][n] = __builtin_amdgcn_mfma_f32_16x16x32_bf16(Bt[n][k], At[m][k], acc[ai][bj][m][n], 0, 0, 0); __builtin_amdgcn_s_setprio(0); } while (0)
; #define PG8_WAIT_V(n) asm volatile("s_waitcnt vmcnt(" #n ")" ::: "memory")
; #define PG8_WAIT_L(n) asm volatile("s_waitcnt lgkmcnt(" #n ")" ::: "memory")
; #define PG8_BAR __builtin_amdgcn_s_barrier()
; #define PG8_SCHED __builtin_amdgcn_sched_barrier(0)
; template <class Epi, class Sched, bool ALIGN_EPI = false, bool SP2 = false>
; __device__ __forceinline__ void gemm_phase(PG8_LAS unsigned char* lds, const Gemm g, const Sched& S, const Epi& E) {
;     ...
;             PG8_LDB(B0, 1, 0); PG8_LDB(B1, 1, 1); PG8_SCHED; PG8_LDA(At, 1, 0); PG8_STAGE(PG8_SA(0, 1), a2 + hstep, voffA);
;             PG8_WAIT_V(8); PG8_WAIT_L(0); PG8_BAR; PG8_MMA(0, 0, At, B0); PG8_MMA(0, 1, At, B1); PG8_BAR; PG8_SCHED;
;             PG8_LDA(At, 1, 1); PG8_STAGE(PG8_SB(1, 0), b3, voffB); PG8_STAGE(PG8_SB(1, 1), b3 + hstep, voffB); PG8_STAGE(PG8_SA(1, 0), a3, voffA);
;             PG8_WAIT_V(8); PG8_WAIT_L(0); PG8_BAR; PG8_MMA(1, 0, At, B0); PG8_MMA(1, 1, At, B1); PG8_BAR; PG8_SCHED;
.Lkmid_3:
	ds_read_b128 v[68:71], v234 offset:32768
	ds_read_b128 v[80:83], v234 offset:33792
	ds_read_b128 v[92:95], v234 offset:34816
	ds_read_b128 v[100:103], v234 offset:35840
	ds_read_b128 v[112:115], v234 offset:49152
	ds_read_b128 v[120:123], v234 offset:50176
	ds_read_b128 v[132:135], v234 offset:51200
	ds_read_b128 v[144:147], v234 offset:52224
	s_mov_b32 m0, s40
	s_add_u32 s26, s30, 0xb0000
	s_addc_u32 s27, s31, 0
	global_load_lds_dwordx4 v[214:215], off
	s_mov_b32 m0, s41
	v_lshl_add_u64 v[218:219], s[26:27], 0, v[0:1]
	global_load_lds_dwordx4 v[216:217], off
	s_mov_b32 m0, s42
	ds_read_b128 v[156:159], v236 offset:32768
	ds_read_b128 v[168:171], v236 offset:33792
	ds_read_b128 v[172:175], v236 offset:34816
	ds_read_b128 v[176:179], v236 offset:35840
	ds_read_b128 v[180:183], v236 offset:36864
	ds_read_b128 v[184:187], v236 offset:37888
	ds_read_b128 v[188:191], v236 offset:38912
	ds_read_b128 v[208:211], v236 offset:39936
	global_load_lds_dwordx4 v[218:219], off
	s_mov_b32 m0, s43
	v_lshl_add_u64 v[218:219], s[26:27], 0, v[194:195]
	global_load_lds_dwordx4 v[218:219], off
	s_waitcnt vmcnt(8) lgkmcnt(0)
	s_barrier
	s_setprio 1
	v_mfma_f32_16x16x32_bf16 v[164:167], v[68:71], v[156:159], v[164:167]
	v_mfma_f32_16x16x32_bf16 v[160:163], v[92:95], v[156:159], v[160:163]
	v_mfma_f32_16x16x32_bf16 v[140:143], v[68:71], v[172:175], v[140:143]
	v_mfma_f32_16x16x32_bf16 v[136:139], v[92:95], v[172:175], v[136:139]
	v_mfma_f32_16x16x32_bf16 v[116:119], v[68:71], v[180:183], v[116:119]
	v_mfma_f32_16x16x32_bf16 v[108:111], v[92:95], v[180:183], v[108:111]
	v_mfma_f32_16x16x32_bf16 v[88:91], v[68:71], v[188:191], v[88:91]
	v_mfma_f32_16x16x32_bf16 v[84:87], v[92:95], v[188:191], v[84:87]
	v_mfma_f32_16x16x32_bf16 v[164:167], v[80:83], v[168:171], v[164:167]
	v_mfma_f32_16x16x32_bf16 v[160:163], v[100:103], v[168:171], v[160:163]
	v_mfma_f32_16x16x32_bf16 v[140:143], v[80:83], v[176:179], v[140:143]
	v_mfma_f32_16x16x32_bf16 v[136:139], v[100:103], v[176:179], v[136:139]
	v_mfma_f32_16x16x32_bf16 v[116:119], v[80:83], v[184:187], v[116:119]
	v_mfma_f32_16x16x32_bf16 v[108:111], v[100:103], v[184:187], v[108:111]
	v_mfma_f32_16x16x32_bf16 v[88:91], v[80:83], v[208:211], v[88:91]
	v_mfma_f32_16x16x32_bf16 v[84:87], v[100:103], v[208:211], v[84:87]
	s_setprio 0
	s_setprio 1
	v_mfma_f32_16x16x32_bf16 v[152:155], v[112:115], v[156:159], v[152:155]
	v_mfma_f32_16x16x32_bf16 v[148:151], v[132:135], v[156:159], v[148:151]
	v_mfma_f32_16x16x32_bf16 v[128:131], v[112:115], v[172:175], v[128:131]
	v_mfma_f32_16x16x32_bf16 v[124:127], v[132:135], v[172:175], v[124:127]
	v_mfma_f32_16x16x32_bf16 v[104:107], v[112:115], v[180:183], v[104:107]
	v_mfma_f32_16x16x32_bf16 v[96:99], v[132:135], v[180:183], v[96:99]
	v_mfma_f32_16x16x32_bf16 v[76:79], v[112:115], v[188:191], v[76:79]
	v_mfma_f32_16x16x32_bf16 v[72:75], v[132:135], v[188:191], v[72:75]
	v_mfma_f32_16x16x32_bf16 v[152:155], v[120:123], v[168:171], v[152:155]
	v_mfma_f32_16x16x32_bf16 v[148:151], v[144:147], v[168:171], v[148:151]
	v_mfma_f32_16x16x32_bf16 v[128:131], v[120:123], v[176:179], v[128:131]
	v_mfma_f32_16x16x32_bf16 v[124:127], v[144:147], v[176:179], v[124:127]
	v_mfma_f32_16x16x32_bf16 v[104:107], v[120:123], v[184:187], v[104:107]
	v_mfma_f32_16x16x32_bf16 v[96:99], v[144:147], v[184:187], v[96:99]
	v_mfma_f32_16x16x32_bf16 v[76:79], v[120:123], v[208:211], v[76:79]
	v_mfma_f32_16x16x32_bf16 v[72:75], v[144:147], v[208:211], v[72:75]
	s_setprio 0
	s_barrier
	s_add_i32 m0, s39, 0x17f80
	ds_read_b128 v[156:159], v236 offset:49152
	ds_read_b128 v[168:171], v236 offset:50176
	ds_read_b128 v[172:175], v236 offset:51200
	ds_read_b128 v[176:179], v236 offset:52224
	ds_read_b128 v[180:183], v236 offset:53248
	ds_read_b128 v[184:187], v236 offset:54272
	ds_read_b128 v[188:191], v236 offset:55296
	ds_read_b128 v[208:211], v236 offset:56320
	global_load_lds_dwordx4 v[198:199], off offset:128
	s_add_i32 m0, s39, 0x19f80
	s_add_u32 s26, s28, 0xb0080
	s_addc_u32 s27, s29, 0
	global_load_lds_dwordx4 v[212:213], off offset:128
	s_add_i32 m0, s39, 0x1c000
	v_lshl_add_u64 v[198:199], s[26:27], 0, v[192:193]
	global_load_lds_dwordx4 v[198:199], off
	s_add_i32 m0, s39, 0x1e000
	v_lshl_add_u64 v[198:199], s[26:27], 0, v[202:203]
	global_load_lds_dwordx4 v[198:199], off
	s_cmp_eq_u32 s53, 40
	s_cbranch_scc0 .Lks4_3
	s_add_i32 m0, s47, 0xffffff80
	s_nop 0
	global_load_lds_dwordx4 v[214:215], off offset:128
	s_add_i32 m0, s48, 0xffffff80
	s_nop 0
	global_load_lds_dwordx4 v[216:217], off offset:128
.Lks4_3:
	s_add_u32 s44, s44, 0x100
	s_addc_u32 s45, s45, 0
	s_mov_b64 s[26:27], s[8:9]
	s_waitcnt vmcnt(6) lgkmcnt(0)
	s_barrier
	s_setprio 1
	v_mfma_f32_16x16x32_bf16 v[64:67], v[68:71], v[156:159], v[64:67]
	v_mfma_f32_16x16x32_bf16 v[60:63], v[92:95], v[156:159], v[60:63]
	v_mfma_f32_16x16x32_bf16 v[48:51], v[68:71], v[172:175], v[48:51]
	v_mfma_f32_16x16x32_bf16 v[44:47], v[92:95], v[172:175], v[44:47]
	v_mfma_f32_16x16x32_bf16 v[32:35], v[68:71], v[180:183], v[32:35]
	v_mfma_f32_16x16x32_bf16 v[28:31], v[92:95], v[180:183], v[28:31]
	v_mfma_f32_16x16x32_bf16 v[16:19], v[68:71], v[188:191], v[16:19]
	v_mfma_f32_16x16x32_bf16 v[12:15], v[92:95], v[188:191], v[12:15]
	v_mfma_f32_16x16x32_bf16 v[64:67], v[80:83], v[168:171], v[64:67]
	v_mfma_f32_16x16x32_bf16 v[60:63], v[100:103], v[168:171], v[60:63]
	v_mfma_f32_16x16x32_bf16 v[48:51], v[80:83], v[176:179], v[48:51]
	v_mfma_f32_16x16x32_bf16 v[44:47], v[100:103], v[176:179], v[44:47]
	v_mfma_f32_16x16x32_bf16 v[32:35], v[80:83], v[184:187], v[32:35]
	v_mfma_f32_16x16x32_bf16 v[28:31], v[100:103], v[184:187], v[28:31]
	v_mfma_f32_16x16x32_bf16 v[16:19], v[80:83], v[208:211], v[16:19]
	v_mfma_f32_16x16x32_bf16 v[12:15], v[100:103], v[208:211], v[12:15]
	s_setprio 0
	s_setprio 1
	v_mfma_f32_16x16x32_bf16 v[56:59], v[112:115], v[156:159], v[56:59]
	v_mfma_f32_16x16x32_bf16 v[52:55], v[132:135], v[156:159], v[52:55]
	v_mfma_f32_16x16x32_bf16 v[40:43], v[112:115], v[172:175], v[40:43]
	v_mfma_f32_16x16x32_bf16 v[36:39], v[132:135], v[172:175], v[36:39]
	v_mfma_f32_16x16x32_bf16 v[24:27], v[112:115], v[180:183], v[24:27]
	v_mfma_f32_16x16x32_bf16 v[20:23], v[132:135], v[180:183], v[20:23]
	v_mfma_f32_16x16x32_bf16 v[8:11], v[112:115], v[188:191], v[8:11]
	v_mfma_f32_16x16x32_bf16 v[4:7], v[132:135], v[188:191], v[4:7]
	v_mfma_f32_16x16x32_bf16 v[56:59], v[120:123], v[168:171], v[56:59]
	v_mfma_f32_16x16x32_bf16 v[52:55], v[144:147], v[168:171], v[52:55]
	v_mfma_f32_16x16x32_bf16 v[40:43], v[120:123], v[176:179], v[40:43]
	v_mfma_f32_16x16x32_bf16 v[36:39], v[144:147], v[176:179], v[36:39]
	v_mfma_f32_16x16x32_bf16 v[24:27], v[120:123], v[184:187], v[24:27]
	v_mfma_f32_16x16x32_bf16 v[20:23], v[144:147], v[184:187], v[20:23]
	v_mfma_f32_16x16x32_bf16 v[8:11], v[120:123], v[208:211], v[8:11]
	v_mfma_f32_16x16x32_bf16 v[4:7], v[144:147], v[208:211], v[4:7]
	s_setprio 0
	s_barrier
	s_add_i32 s53, s53, 2
	s_cmp_gt_u32 s53, 41
	s_cbranch_scc0 .LBB0_480
	s_and_b64 vcc, exec, s[20:21]
	s_cbranch_vccz .LBB0_483
	s_barrier
